# speedup vs baseline: 1.0276x; 1.0080x over previous
; #define PG8_STAGE(bufoff, gbase, voff) do { _Pragma("unroll") for (int _i = 0; _i < 2; ++_i) \
;         __builtin_amdgcn_global_load_lds((const unsigned*)((const char*)(gbase) + (voff)[_i]), (PG8_LAS unsigned*)(lds + (bufoff) + ldsw + _i * 8192), 16, 0, 0); } while (0)
; #define PG8_LDA(dst, b, h) do { _Pragma("unroll") for (int m = 0; m < 4; ++m) _Pragma("unroll") for (int k = 0; k < 2; ++k) dst[m][k] = *(const PG8_LAS bf16x8*)(lds + PG8_SA(b, h) + aoff + m * 2048 + k * 1024); } while (0)
; #define PG8_LDB(dst, b, h) do { _Pragma("unroll") for (int n = 0; n < 2; ++n) _Pragma("unroll") for (int k = 0; k < 2; ++k) dst[n][k] = *(const PG8_LAS bf16x8*)(lds + PG8_SB(b, h) + boff + n * 2048 + k * 1024); } while (0)
; #define PG8_MMA(ai, bj, At, Bt) do { __builtin_amdgcn_s_setprio(1); _Pragma("unroll") for (int m = 0; m < 4; ++m) _Pragma("unroll") for (int n = 0; n < 2; ++n) _Pragma("unroll") for (int k = 0; k < 2; ++k) \
;         acc[ai][bj][m][n] = __builtin_amdgcn_mfma_f32_16x16x32_bf16(Bt[n][k], At[m][k], acc[ai][bj][m][n], 0, 0, 0); __builtin_amdgcn_s_setprio(0); } while (0)
; #define PG8_WAIT_L(n) asm volatile("s_waitcnt lgkmcnt(" #n ")" ::: "memory")
; #define PG8_BAR __builtin_amdgcn_s_barrier()
; #define PG8_SCHED __builtin_amdgcn_sched_barrier(0)
; template <class Epi, class Sched>
; __device__ __forceinline__ void gemm_phase(PG8_LAS unsigned char* lds, const Gemm g, const Sched& S, const Epi& E) {
;     ...
;             PG8_LDB(B0, 0, 0); PG8_SCHED; PG8_LDA(At, 0, 0); PG8_STAGE(PG8_SA(1, 1), a1 + hstep, voffA);
;             PG8_WAIT_L(8); PG8_BAR; PG8_WAIT_L(0); PG8_MMA(0, 0, At, B0); PG8_BAR; PG8_SCHED;
;             PG8_LDB(B1, 0, 1); PG8_STAGE(PG8_SB(0, 0), b2, voffB);
;             PG8_BAR; PG8_WAIT_L(0); PG8_MMA(0, 1, At, B1); PG8_BAR;
;             PG8_LDA(At, 0, 1); PG8_STAGE(PG8_SA(0, 0), a2, voffA);
;             PG8_BAR; PG8_WAIT_L(0); PG8_MMA(1, 0, At, B0); PG8_BAR; PG8_SCHED;
.LBB0_872:
	ds_read_b128 v[148:151], v162
	ds_read_b128 v[166:169], v162 offset:1024
	ds_read_b128 v[170:173], v162 offset:2048
	ds_read_b128 v[174:177], v162 offset:3072
	s_add_u32 s20, s18, 0xfff80080
	s_addc_u32 s21, s19, -1
	s_cmp_eq_u32 s55, 28
	s_cselect_b32 s23, s11, s21
	s_cselect_b32 s22, s51, s20
	s_cselect_b32 s21, s9, s54
	s_cselect_b32 s20, s52, s53
	v_lshl_add_u64 v[210:211], s[18:19], 0, v[136:137]
	s_add_i32 m0, s17, 0xc000
	ds_read_b128 v[178:181], v163
	ds_read_b128 v[182:185], v163 offset:1024
	ds_read_b128 v[186:189], v163 offset:2048
	ds_read_b128 v[190:193], v163 offset:3072
	ds_read_b128 v[194:197], v163 offset:4096
	ds_read_b128 v[198:201], v163 offset:5120
	ds_read_b128 v[202:205], v163 offset:6144
	ds_read_b128 v[206:209], v163 offset:7168
	global_load_lds_dwordx4 v[210:211], off
	v_lshl_add_u64 v[210:211], s[18:19], 0, v[138:139]
	s_add_i32 m0, s17, 0xe000
	s_nop 0
	global_load_lds_dwordx4 v[210:211], off
	s_waitcnt lgkmcnt(8)
	s_barrier
	s_waitcnt lgkmcnt(0)
	s_waitcnt lgkmcnt(0)
	v_mfma_f32_16x16x32_bf16 v[124:127], v[148:151], v[178:181], v[124:127]
	v_mfma_f32_16x16x32_bf16 v[120:123], v[170:173], v[178:181], v[120:123]
	v_mfma_f32_16x16x32_bf16 v[112:115], v[148:151], v[186:189], v[112:115]
	v_mfma_f32_16x16x32_bf16 v[104:107], v[170:173], v[186:189], v[104:107]
	v_mfma_f32_16x16x32_bf16 v[96:99], v[148:151], v[194:197], v[96:99]
	v_mfma_f32_16x16x32_bf16 v[88:91], v[170:173], v[194:197], v[88:91]
	v_mfma_f32_16x16x32_bf16 v[80:83], v[148:151], v[202:205], v[80:83]
	v_mfma_f32_16x16x32_bf16 v[72:75], v[170:173], v[202:205], v[72:75]
	v_mfma_f32_16x16x32_bf16 v[124:127], v[166:169], v[182:185], v[124:127]
	v_mfma_f32_16x16x32_bf16 v[120:123], v[174:177], v[182:185], v[120:123]
	v_mfma_f32_16x16x32_bf16 v[112:115], v[166:169], v[190:193], v[112:115]
	v_mfma_f32_16x16x32_bf16 v[104:107], v[174:177], v[190:193], v[104:107]
	v_mfma_f32_16x16x32_bf16 v[96:99], v[166:169], v[198:201], v[96:99]
	v_mfma_f32_16x16x32_bf16 v[88:91], v[174:177], v[198:201], v[88:91]
	v_mfma_f32_16x16x32_bf16 v[80:83], v[166:169], v[206:209], v[80:83]
	v_mfma_f32_16x16x32_bf16 v[72:75], v[174:177], v[206:209], v[72:75]
	s_barrier
	s_add_i32 s30, s48, s27
	v_lshl_add_u64 v[226:227], s[20:21], 0, v[130:131]
	s_mov_b32 m0, s30
	ds_read_b128 v[210:213], v164
	ds_read_b128 v[214:217], v164 offset:1024
	ds_read_b128 v[218:221], v164 offset:2048
	ds_read_b128 v[222:225], v164 offset:3072
	global_load_lds_dwordx4 v[226:227], off
	v_lshl_add_u64 v[228:229], s[20:21], 0, v[134:135]
	s_add_i32 m0, s30, 0x2000
	s_nop 0
	global_load_lds_dwordx4 v[228:229], off
	s_barrier
	s_waitcnt lgkmcnt(0)
	s_waitcnt lgkmcnt(0)
	v_mfma_f32_16x16x32_bf16 v[116:119], v[210:213], v[178:181], v[116:119]
	v_mfma_f32_16x16x32_bf16 v[108:111], v[218:221], v[178:181], v[108:111]
	v_mfma_f32_16x16x32_bf16 v[100:103], v[210:213], v[186:189], v[100:103]
	v_mfma_f32_16x16x32_bf16 v[92:95], v[218:221], v[186:189], v[92:95]
	v_mfma_f32_16x16x32_bf16 v[84:87], v[210:213], v[194:197], v[84:87]
	v_mfma_f32_16x16x32_bf16 v[76:79], v[218:221], v[194:197], v[76:79]
	v_mfma_f32_16x16x32_bf16 v[68:71], v[210:213], v[202:205], v[68:71]
	v_mfma_f32_16x16x32_bf16 v[64:67], v[218:221], v[202:205], v[64:67]
	v_mfma_f32_16x16x32_bf16 v[116:119], v[214:217], v[182:185], v[116:119]
	v_mfma_f32_16x16x32_bf16 v[108:111], v[222:225], v[182:185], v[108:111]
	v_mfma_f32_16x16x32_bf16 v[100:103], v[214:217], v[190:193], v[100:103]
	v_mfma_f32_16x16x32_bf16 v[92:95], v[222:225], v[190:193], v[92:95]
	v_mfma_f32_16x16x32_bf16 v[84:87], v[214:217], v[198:201], v[84:87]
	v_mfma_f32_16x16x32_bf16 v[76:79], v[222:225], v[198:201], v[76:79]
	v_mfma_f32_16x16x32_bf16 v[68:71], v[214:217], v[206:209], v[68:71]
	v_mfma_f32_16x16x32_bf16 v[64:67], v[222:225], v[206:209], v[64:67]
	s_mov_b32 m0, s17
	v_lshl_add_u64 v[230:231], s[22:23], 0, v[128:129]
	s_barrier
	ds_read_b128 v[178:181], v163 offset:16384
	ds_read_b128 v[182:185], v163 offset:17408
	ds_read_b128 v[186:189], v163 offset:18432
	ds_read_b128 v[190:193], v163 offset:19456
	ds_read_b128 v[194:197], v163 offset:20480
	ds_read_b128 v[198:201], v163 offset:21504
	ds_read_b128 v[202:205], v163 offset:22528
	ds_read_b128 v[206:209], v163 offset:23552
	global_load_lds_dwordx4 v[230:231], off
	v_lshl_add_u64 v[232:233], s[22:23], 0, v[132:133]
	s_mov_b32 m0, s28
	s_nop 0
	global_load_lds_dwordx4 v[232:233], off
	s_barrier
	s_waitcnt lgkmcnt(0)
	s_waitcnt lgkmcnt(0)
	v_mfma_f32_16x16x32_bf16 v[60:63], v[148:151], v[178:181], v[60:63]
	v_mfma_f32_16x16x32_bf16 v[56:59], v[170:173], v[178:181], v[56:59]
	v_mfma_f32_16x16x32_bf16 v[52:55], v[148:151], v[186:189], v[52:55]
	v_mfma_f32_16x16x32_bf16 v[44:47], v[170:173], v[186:189], v[44:47]
	v_mfma_f32_16x16x32_bf16 v[36:39], v[148:151], v[194:197], v[36:39]
	v_mfma_f32_16x16x32_bf16 v[28:31], v[170:173], v[194:197], v[28:31]
	v_mfma_f32_16x16x32_bf16 v[20:23], v[148:151], v[202:205], v[20:23]
	v_mfma_f32_16x16x32_bf16 v[12:15], v[170:173], v[202:205], v[12:15]
	v_mfma_f32_16x16x32_bf16 v[60:63], v[166:169], v[182:185], v[60:63]
	v_mfma_f32_16x16x32_bf16 v[56:59], v[174:177], v[182:185], v[56:59]
	v_mfma_f32_16x16x32_bf16 v[52:55], v[166:169], v[190:193], v[52:55]
	v_mfma_f32_16x16x32_bf16 v[44:47], v[174:177], v[190:193], v[44:47]
	v_mfma_f32_16x16x32_bf16 v[36:39], v[166:169], v[198:201], v[36:39]
	v_mfma_f32_16x16x32_bf16 v[28:31], v[174:177], v[198:201], v[28:31]
	v_mfma_f32_16x16x32_bf16 v[20:23], v[166:169], v[206:209], v[20:23]
	v_mfma_f32_16x16x32_bf16 v[12:15], v[174:177], v[206:209], v[12:15]
	s_barrier
; #define PG8_STAGE(bufoff, gbase, voff) do { _Pragma("unroll") for (int _i = 0; _i < 2; ++_i) \
;         __builtin_amdgcn_global_load_lds((const unsigned*)((const char*)(gbase) + (voff)[_i]), (PG8_LAS unsigned*)(lds + (bufoff) + ldsw + _i * 8192), 16, 0, 0); } while (0)
; #define PG8_LDA(dst, b, h) do { _Pragma("unroll") for (int m = 0; m < 4; ++m) _Pragma("unroll") for (int k = 0; k < 2; ++k) dst[m][k] = *(const PG8_LAS bf16x8*)(lds + PG8_SA(b, h) + aoff + m * 2048 + k * 1024); } while (0)
; #define PG8_LDB(dst, b, h) do { _Pragma("unroll") for (int n = 0; n < 2; ++n) _Pragma("unroll") for (int k = 0; k < 2; ++k) dst[n][k] = *(const PG8_LAS bf16x8*)(lds + PG8_SB(b, h) + boff + n * 2048 + k * 1024); } while (0)
; #define PG8_MMA(ai, bj, At, Bt) do { __builtin_amdgcn_s_setprio(1); _Pragma("unroll") for (int m = 0; m < 4; ++m) _Pragma("unroll") for (int n = 0; n < 2; ++n) _Pragma("unroll") for (int k = 0; k < 2; ++k) \
;         acc[ai][bj][m][n] = __builtin_amdgcn_mfma_f32_16x16x32_bf16(Bt[n][k], At[m][k], acc[ai][bj][m][n], 0, 0, 0); __builtin_amdgcn_s_setprio(0); } while (0)
; #define PG8_WAIT_V(n) asm volatile("s_waitcnt vmcnt(" #n ")" ::: "memory")
; #define PG8_WAIT_L(n) asm volatile("s_waitcnt lgkmcnt(" #n ")" ::: "memory")
; #define PG8_BAR __builtin_amdgcn_s_barrier()
; #define PG8_SCHED __builtin_amdgcn_sched_barrier(0)
; template <class Epi, class Sched>
; __device__ __forceinline__ void gemm_phase(PG8_LAS unsigned char* lds, const Gemm g, const Sched& S, const Epi& E) {
;     ...
;             PG8_STAGE(PG8_SB(0, 1), b2 + hstep, voffB);
;             PG8_WAIT_V(6); PG8_BAR; PG8_MMA(1, 1, At, B1); PG8_BAR;
;             PG8_LDB(B0, 1, 0); PG8_SCHED; PG8_LDA(At, 1, 0); PG8_STAGE(PG8_SA(0, 1), a2 + hstep, voffA);
;             PG8_WAIT_L(8); PG8_BAR; PG8_WAIT_L(0); PG8_MMA(0, 0, At, B0); PG8_BAR; PG8_SCHED;
;             PG8_LDB(B1, 1, 1); PG8_STAGE(PG8_SB(1, 0), b3, voffB);
;             PG8_BAR; PG8_WAIT_L(0); PG8_MMA(0, 1, At, B1); PG8_BAR;
;             PG8_LDA(At, 1, 1); PG8_STAGE(PG8_SA(1, 0), a3, voffA);
	s_add_u32 s30, s20, 0x80000
	s_addc_u32 s31, s21, 0
	s_add_i32 s38, s49, s27
	v_lshl_add_u64 v[148:149], s[30:31], 0, v[130:131]
	s_mov_b32 m0, s38
	s_nop 0
	global_load_lds_dwordx4 v[148:149], off
	v_lshl_add_u64 v[148:149], s[30:31], 0, v[134:135]
	s_add_i32 m0, s38, 0x2000
	s_nop 0
	global_load_lds_dwordx4 v[148:149], off
	s_waitcnt vmcnt(6)
	s_barrier
	v_mfma_f32_16x16x32_bf16 v[48:51], v[210:213], v[178:181], v[48:51]
	v_mfma_f32_16x16x32_bf16 v[40:43], v[218:221], v[178:181], v[40:43]
	v_mfma_f32_16x16x32_bf16 v[32:35], v[210:213], v[186:189], v[32:35]
	v_mfma_f32_16x16x32_bf16 v[24:27], v[218:221], v[186:189], v[24:27]
	v_mfma_f32_16x16x32_bf16 v[16:19], v[210:213], v[194:197], v[16:19]
	v_mfma_f32_16x16x32_bf16 v[8:11], v[218:221], v[194:197], v[8:11]
	v_mfma_f32_16x16x32_bf16 v[4:7], v[210:213], v[202:205], v[4:7]
	v_mfma_f32_16x16x32_bf16 v[0:3], v[218:221], v[202:205], v[0:3]
	v_mfma_f32_16x16x32_bf16 v[48:51], v[214:217], v[182:185], v[48:51]
	v_mfma_f32_16x16x32_bf16 v[40:43], v[222:225], v[182:185], v[40:43]
	v_mfma_f32_16x16x32_bf16 v[32:35], v[214:217], v[190:193], v[32:35]
	v_mfma_f32_16x16x32_bf16 v[24:27], v[222:225], v[190:193], v[24:27]
	v_mfma_f32_16x16x32_bf16 v[16:19], v[214:217], v[198:201], v[16:19]
	v_mfma_f32_16x16x32_bf16 v[8:11], v[222:225], v[198:201], v[8:11]
	v_mfma_f32_16x16x32_bf16 v[4:7], v[214:217], v[206:209], v[4:7]
	v_mfma_f32_16x16x32_bf16 v[0:3], v[222:225], v[206:209], v[0:3]
	s_add_i32 s30, 0, 0x18000
	v_add_u32_e32 v165, s30, v160
	s_barrier
	ds_read_b128 v[148:151], v165
	ds_read_b128 v[166:169], v165 offset:1024
	ds_read_b128 v[170:173], v165 offset:2048
	ds_read_b128 v[174:177], v165 offset:3072
	s_add_u32 s22, s22, 0x80000
	s_addc_u32 s23, s23, 0
	s_mov_b32 m0, s29
	v_lshl_add_u64 v[210:211], s[22:23], 0, v[128:129]
	ds_read_b128 v[178:181], v163 offset:32768
	ds_read_b128 v[182:185], v163 offset:33792
	ds_read_b128 v[186:189], v163 offset:34816
	ds_read_b128 v[190:193], v163 offset:35840
	ds_read_b128 v[194:197], v163 offset:36864
	ds_read_b128 v[198:201], v163 offset:37888
	ds_read_b128 v[202:205], v163 offset:38912
	ds_read_b128 v[206:209], v163 offset:39936
	global_load_lds_dwordx4 v[210:211], off
	v_lshl_add_u64 v[210:211], s[22:23], 0, v[132:133]
	s_mov_b32 m0, s42
	s_nop 0
	global_load_lds_dwordx4 v[210:211], off
	s_waitcnt lgkmcnt(8)
	s_barrier
	s_waitcnt lgkmcnt(0)
	s_waitcnt lgkmcnt(0)
	v_mfma_f32_16x16x32_bf16 v[124:127], v[148:151], v[178:181], v[124:127]
	v_mfma_f32_16x16x32_bf16 v[120:123], v[170:173], v[178:181], v[120:123]
	v_mfma_f32_16x16x32_bf16 v[112:115], v[148:151], v[186:189], v[112:115]
	v_mfma_f32_16x16x32_bf16 v[104:107], v[170:173], v[186:189], v[104:107]
	v_mfma_f32_16x16x32_bf16 v[96:99], v[148:151], v[194:197], v[96:99]
	v_mfma_f32_16x16x32_bf16 v[88:91], v[170:173], v[194:197], v[88:91]
	v_mfma_f32_16x16x32_bf16 v[80:83], v[148:151], v[202:205], v[80:83]
	v_mfma_f32_16x16x32_bf16 v[72:75], v[170:173], v[202:205], v[72:75]
	v_mfma_f32_16x16x32_bf16 v[124:127], v[166:169], v[182:185], v[124:127]
	v_mfma_f32_16x16x32_bf16 v[120:123], v[174:177], v[182:185], v[120:123]
	v_mfma_f32_16x16x32_bf16 v[112:115], v[166:169], v[190:193], v[112:115]
	v_mfma_f32_16x16x32_bf16 v[104:107], v[174:177], v[190:193], v[104:107]
	v_mfma_f32_16x16x32_bf16 v[96:99], v[166:169], v[198:201], v[96:99]
	v_mfma_f32_16x16x32_bf16 v[88:91], v[174:177], v[198:201], v[88:91]
	v_mfma_f32_16x16x32_bf16 v[80:83], v[166:169], v[206:209], v[80:83]
	v_mfma_f32_16x16x32_bf16 v[72:75], v[174:177], v[206:209], v[72:75]
	s_barrier
	s_add_i32 s22, 0, 0x1c000
	s_add_i32 s23, s30, s27
	v_add_u32_e32 v165, s22, v160
	v_lshl_add_u64 v[226:227], v[226:227], 0, s[6:7]
	s_mov_b32 m0, s23
	ds_read_b128 v[210:213], v165
	ds_read_b128 v[214:217], v165 offset:1024
	ds_read_b128 v[218:221], v165 offset:2048
	ds_read_b128 v[222:225], v165 offset:3072
	global_load_lds_dwordx4 v[226:227], off
	v_lshl_add_u64 v[226:227], v[228:229], 0, s[6:7]
	s_add_i32 m0, s23, 0x2000
	s_nop 0
	global_load_lds_dwordx4 v[226:227], off
	s_barrier
	s_waitcnt lgkmcnt(0)
	s_waitcnt lgkmcnt(0)
	v_mfma_f32_16x16x32_bf16 v[116:119], v[210:213], v[178:181], v[116:119]
	v_mfma_f32_16x16x32_bf16 v[108:111], v[218:221], v[178:181], v[108:111]
	v_mfma_f32_16x16x32_bf16 v[100:103], v[210:213], v[186:189], v[100:103]
	v_mfma_f32_16x16x32_bf16 v[92:95], v[218:221], v[186:189], v[92:95]
	v_mfma_f32_16x16x32_bf16 v[84:87], v[210:213], v[194:197], v[84:87]
	v_mfma_f32_16x16x32_bf16 v[76:79], v[218:221], v[194:197], v[76:79]
	v_mfma_f32_16x16x32_bf16 v[68:71], v[210:213], v[202:205], v[68:71]
	v_mfma_f32_16x16x32_bf16 v[64:67], v[218:221], v[202:205], v[64:67]
	v_mfma_f32_16x16x32_bf16 v[116:119], v[214:217], v[182:185], v[116:119]
	v_mfma_f32_16x16x32_bf16 v[108:111], v[222:225], v[182:185], v[108:111]
	v_mfma_f32_16x16x32_bf16 v[100:103], v[214:217], v[190:193], v[100:103]
	v_mfma_f32_16x16x32_bf16 v[92:95], v[222:225], v[190:193], v[92:95]
	v_mfma_f32_16x16x32_bf16 v[84:87], v[214:217], v[198:201], v[84:87]
	v_mfma_f32_16x16x32_bf16 v[76:79], v[222:225], v[198:201], v[76:79]
	v_mfma_f32_16x16x32_bf16 v[68:71], v[214:217], v[206:209], v[68:71]
	v_mfma_f32_16x16x32_bf16 v[64:67], v[222:225], v[206:209], v[64:67]
	s_mov_b32 m0, s44
	v_lshl_add_u64 v[226:227], v[230:231], 0, s[6:7]
	s_barrier
	ds_read_b128 v[178:181], v163 offset:49152
	ds_read_b128 v[182:185], v163 offset:50176
	ds_read_b128 v[186:189], v163 offset:51200
	ds_read_b128 v[190:193], v163 offset:52224
	ds_read_b128 v[194:197], v163 offset:53248
	ds_read_b128 v[198:201], v163 offset:54272
	ds_read_b128 v[202:205], v163 offset:55296
	ds_read_b128 v[206:209], v163 offset:56320
	global_load_lds_dwordx4 v[226:227], off
	v_lshl_add_u64 v[226:227], v[232:233], 0, s[6:7]
	s_mov_b32 m0, s45
	s_nop 0
	global_load_lds_dwordx4 v[226:227], off
	s_barrier
; #define PG8_STAGE(bufoff, gbase, voff) do { _Pragma("unroll") for (int _i = 0; _i < 2; ++_i) \
;         __builtin_amdgcn_global_load_lds((const unsigned*)((const char*)(gbase) + (voff)[_i]), (PG8_LAS unsigned*)(lds + (bufoff) + ldsw + _i * 8192), 16, 0, 0); } while (0)
; #define PG8_MMA(ai, bj, At, Bt) do { __builtin_amdgcn_s_setprio(1); _Pragma("unroll") for (int m = 0; m < 4; ++m) _Pragma("unroll") for (int n = 0; n < 2; ++n) _Pragma("unroll") for (int k = 0; k < 2; ++k) \
;         acc[ai][bj][m][n] = __builtin_amdgcn_mfma_f32_16x16x32_bf16(Bt[n][k], At[m][k], acc[ai][bj][m][n], 0, 0, 0); __builtin_amdgcn_s_setprio(0); } while (0)
; #define PG8_WAIT_V(n) asm volatile("s_waitcnt vmcnt(" #n ")" ::: "memory")
; #define PG8_WAIT_L(n) asm volatile("s_waitcnt lgkmcnt(" #n ")" ::: "memory")
; #define PG8_BAR __builtin_amdgcn_s_barrier()
; #define PG8_SCHED __builtin_amdgcn_sched_barrier(0)
; template <class Epi, class Sched>
; __device__ __forceinline__ void gemm_phase(PG8_LAS unsigned char* lds, const Gemm g, const Sched& S, const Epi& E) {
;     ...
;         for (int t = 0; t < nt; t += 2) {
;     ...
;             PG8_BAR; PG8_WAIT_L(0); PG8_MMA(1, 0, At, B0); PG8_BAR; PG8_SCHED;
;             PG8_STAGE(PG8_SB(1, 1), b3 + hstep, voffB);
;             PG8_WAIT_V(6); PG8_BAR; PG8_MMA(1, 1, At, B1); PG8_BAR;
	s_waitcnt lgkmcnt(0)
	s_waitcnt lgkmcnt(0)
	v_mfma_f32_16x16x32_bf16 v[60:63], v[148:151], v[178:181], v[60:63]
	v_mfma_f32_16x16x32_bf16 v[56:59], v[170:173], v[178:181], v[56:59]
	v_mfma_f32_16x16x32_bf16 v[52:55], v[148:151], v[186:189], v[52:55]
	v_mfma_f32_16x16x32_bf16 v[44:47], v[170:173], v[186:189], v[44:47]
	v_mfma_f32_16x16x32_bf16 v[36:39], v[148:151], v[194:197], v[36:39]
	v_mfma_f32_16x16x32_bf16 v[28:31], v[170:173], v[194:197], v[28:31]
	v_mfma_f32_16x16x32_bf16 v[20:23], v[148:151], v[202:205], v[20:23]
	v_mfma_f32_16x16x32_bf16 v[12:15], v[170:173], v[202:205], v[12:15]
	v_mfma_f32_16x16x32_bf16 v[60:63], v[166:169], v[182:185], v[60:63]
	v_mfma_f32_16x16x32_bf16 v[56:59], v[174:177], v[182:185], v[56:59]
	v_mfma_f32_16x16x32_bf16 v[52:55], v[166:169], v[190:193], v[52:55]
	v_mfma_f32_16x16x32_bf16 v[44:47], v[174:177], v[190:193], v[44:47]
	v_mfma_f32_16x16x32_bf16 v[36:39], v[166:169], v[198:201], v[36:39]
	v_mfma_f32_16x16x32_bf16 v[28:31], v[174:177], v[198:201], v[28:31]
	v_mfma_f32_16x16x32_bf16 v[20:23], v[166:169], v[206:209], v[20:23]
	v_mfma_f32_16x16x32_bf16 v[12:15], v[174:177], v[206:209], v[12:15]
	s_barrier
	s_add_u32 s20, s20, 0x80080
	s_addc_u32 s21, s21, 0
	s_add_i32 s22, s22, s27
	v_lshl_add_u64 v[148:149], s[20:21], 0, v[130:131]
	s_mov_b32 m0, s22
	s_nop 0
	global_load_lds_dwordx4 v[148:149], off
	v_lshl_add_u64 v[148:149], s[20:21], 0, v[134:135]
	s_add_i32 m0, s22, 0x2000
	s_nop 0
	global_load_lds_dwordx4 v[148:149], off
	s_waitcnt vmcnt(6)
	s_barrier
	v_mfma_f32_16x16x32_bf16 v[48:51], v[210:213], v[178:181], v[48:51]
	v_mfma_f32_16x16x32_bf16 v[40:43], v[218:221], v[178:181], v[40:43]
	v_mfma_f32_16x16x32_bf16 v[32:35], v[210:213], v[186:189], v[32:35]
	v_mfma_f32_16x16x32_bf16 v[24:27], v[218:221], v[186:189], v[24:27]
	v_mfma_f32_16x16x32_bf16 v[16:19], v[210:213], v[194:197], v[16:19]
	v_mfma_f32_16x16x32_bf16 v[8:11], v[218:221], v[194:197], v[8:11]
	v_mfma_f32_16x16x32_bf16 v[4:7], v[210:213], v[202:205], v[4:7]
	v_mfma_f32_16x16x32_bf16 v[0:3], v[218:221], v[202:205], v[0:3]
	v_mfma_f32_16x16x32_bf16 v[48:51], v[214:217], v[182:185], v[48:51]
	v_mfma_f32_16x16x32_bf16 v[40:43], v[222:225], v[182:185], v[40:43]
	v_mfma_f32_16x16x32_bf16 v[32:35], v[214:217], v[190:193], v[32:35]
	v_mfma_f32_16x16x32_bf16 v[24:27], v[222:225], v[190:193], v[24:27]
	v_mfma_f32_16x16x32_bf16 v[16:19], v[214:217], v[198:201], v[16:19]
	v_mfma_f32_16x16x32_bf16 v[8:11], v[222:225], v[198:201], v[8:11]
	v_mfma_f32_16x16x32_bf16 v[4:7], v[214:217], v[206:209], v[4:7]
	v_mfma_f32_16x16x32_bf16 v[0:3], v[222:225], v[206:209], v[0:3]
	s_add_i32 s55, s55, 2
	s_add_u32 s18, s18, 0x100
	s_addc_u32 s19, s19, 0
	s_add_u32 s53, s53, 0x100
	s_addc_u32 s54, s54, 0
	s_cmp_gt_u32 s55, 29
	s_barrier
	s_cbranch_scc0 .LBB0_872
; #define PG8_WAIT_V(n) asm volatile("s_waitcnt vmcnt(" #n ")" ::: "memory")
; #define PG8_BAR __builtin_amdgcn_s_barrier()
; __device__ __forceinline__ uint4 pk8(f32x4 a, f32x4 b) { return make_uint4(cvt_pk_bf16(a[0], a[1]), cvt_pk_bf16(a[2], a[3]), cvt_pk_bf16(b[0], b[1]), cvt_pk_bf16(b[2], b[3])); }
; template <class Epi, class Sched>
; __device__ __forceinline__ void gemm_phase(PG8_LAS unsigned char* lds, const Gemm g, const Sched& S, const Epi& E) {
;     ...
;         if (!has_next) break;
; #pragma unroll
;         for (int a = 0; a < 2; ++a)
; #pragma unroll
;             for (int b = 0; b < 2; ++b)
; #pragma unroll
;                 for (int m = 0; m < 4; ++m)
; #pragma unroll
;                     for (int n = 0; n < 2; ++n) acc[a][b][m][n] = (f32x4){0.f, 0.f, 0.f, 0.f};
;         cur = nxt; cA = nA; cB = nB; ++ui;
;     }
;     PG8_WAIT_V(0);
;     if (wr == 0) PG8_BAR;
;     __device__ __forceinline__ void operator()(AccRef acc, const Unit& u, int wr, int wc, int fr, int fq) const {
;         const int pi = u.pn / tpp; bf16_t* base = pi == 0 ? pl[0] : (pi == 1 ? pl[1] : (pi == 2 ? pl[2] : pl[3]));
;         const int cbase = (u.pn - pi * tpp) * 256 + wc * 32 + 8 * fq;
; #pragma unroll
;         for (int ai = 0; ai < 2; ++ai)
; #pragma unroll
;             for (int m = 0; m < 4; ++m) {
;                 const int r = u.pm * 256 + ai * 128 + wr * 64 + m * 16 + fr;
;                 float s = 1.f;
;                 if (SCALE == 1) s = rs[r];
;                 if (SCALE == 2) s = rsqrtf(rs[r] * (1.f / D) + EPS);
;                 bf16_t* rowp = base + (size_t)r * ldc + cbase;
; #pragma unroll
;                 for (int bj = 0; bj < 2; ++bj) *(uint4*)(rowp + bj * 128) = pk8(acc[ai][bj][m][0] * s, acc[ai][bj][m][1] * s);
	s_mul_hi_i32 s9, s50, 0x10624dd3
	s_lshr_b32 s11, s9, 31
	s_lshr_b32 s9, s9, 6
	s_add_i32 s9, s9, s11
	s_mulk_i32 s9, 0x3e8
	s_sub_i32 s9, s50, s9
	v_lshl_or_b32 v148, s9, 8, v161
	v_lshl_add_u32 v150, s16, 8, v159
	v_ashrrev_i32_e32 v149, 31, v148
	v_ashrrev_i32_e32 v151, 31, v150
	v_lshl_add_u64 v[148:149], v[148:149], 1, s[40:41]
	v_bfe_i32 v250, v144, 0, 1
	v_and_b32_e32 v250, 0xfffff040, v250
	v_bfe_u32 v251, v146, 1, 1
	v_mul_u32_u24_e32 v251, 0xf80, v251
	v_add_u32_e32 v250, v250, v251
	v_and_b32_e32 v251, 1, v146
	v_lshl_add_u32 v250, v251, 6, v250
	v_ashrrev_i32_e32 v251, 31, v250
	v_lshl_add_u64 v[148:149], v[250:251], 0, v[148:149]
	v_lshlrev_b64 v[166:167], 12, v[150:151]
	v_lshl_add_u64 v[166:167], v[148:149], 0, v[166:167]
	v_cvt_pk_bf16_f32 v124, v124, v125
	v_cvt_pk_bf16_f32 v125, v126, v127
	v_cvt_pk_bf16_f32 v126, v120, v121
	v_cvt_pk_bf16_f32 v127, v122, v123
	global_store_dwordx4 v[166:167], v[124:127], off
	v_cvt_pk_bf16_f32 v116, v116, v117
	v_cvt_pk_bf16_f32 v117, v118, v119
	v_cvt_pk_bf16_f32 v118, v108, v109
	v_or_b32_e32 v108, 16, v150
	v_ashrrev_i32_e32 v109, 31, v108
	v_lshlrev_b64 v[108:109], 12, v[108:109]
	v_cvt_pk_bf16_f32 v119, v110, v111
	global_store_dwordx4 v[166:167], v[116:119], off offset:256
	s_and_b64 vcc, exec, s[4:5]
	s_mov_b32 s50, s8
	v_lshl_add_u64 v[116:117], v[148:149], 0, v[108:109]
	v_cvt_pk_bf16_f32 v108, v112, v113
	v_cvt_pk_bf16_f32 v109, v114, v115
	v_cvt_pk_bf16_f32 v110, v104, v105
	v_cvt_pk_bf16_f32 v111, v106, v107
	global_store_dwordx4 v[116:117], v[108:111], off
	v_cvt_pk_bf16_f32 v100, v100, v101
	v_cvt_pk_bf16_f32 v101, v102, v103
	v_cvt_pk_bf16_f32 v102, v92, v93
	v_or_b32_e32 v92, 32, v150
	v_ashrrev_i32_e32 v93, 31, v92
	v_lshlrev_b64 v[92:93], 12, v[92:93]
	v_cvt_pk_bf16_f32 v103, v94, v95
	global_store_dwordx4 v[116:117], v[100:103], off offset:256
	s_mov_b32 s16, s10
	s_mov_b64 s[20:21], s[14:15]
	v_lshl_add_u64 v[100:101], v[148:149], 0, v[92:93]
	v_cvt_pk_bf16_f32 v92, v96, v97
	v_cvt_pk_bf16_f32 v93, v98, v99
	v_cvt_pk_bf16_f32 v94, v88, v89
	v_cvt_pk_bf16_f32 v95, v90, v91
	global_store_dwordx4 v[100:101], v[92:95], off
	v_cvt_pk_bf16_f32 v84, v84, v85
	v_cvt_pk_bf16_f32 v85, v86, v87
	v_cvt_pk_bf16_f32 v86, v76, v77
	v_or_b32_e32 v76, 48, v150
	v_ashrrev_i32_e32 v77, 31, v76
	v_lshlrev_b64 v[76:77], 12, v[76:77]
	v_cvt_pk_bf16_f32 v87, v78, v79
	global_store_dwordx4 v[100:101], v[84:87], off offset:256
	s_mov_b64 s[18:19], s[12:13]
	s_nop 0
	v_lshl_add_u64 v[84:85], v[148:149], 0, v[76:77]
	v_cvt_pk_bf16_f32 v76, v80, v81
	v_cvt_pk_bf16_f32 v77, v82, v83
	v_cvt_pk_bf16_f32 v78, v72, v73
	v_cvt_pk_bf16_f32 v79, v74, v75
	global_store_dwordx4 v[84:85], v[76:79], off
	v_cvt_pk_bf16_f32 v68, v68, v69
	v_cvt_pk_bf16_f32 v69, v70, v71
	v_cvt_pk_bf16_f32 v70, v64, v65
	v_add_u32_e32 v64, 0x80, v150
	v_ashrrev_i32_e32 v65, 31, v64
	v_lshlrev_b64 v[64:65], 12, v[64:65]
	v_lshl_add_u64 v[64:65], v[148:149], 0, v[64:65]
	v_cvt_pk_bf16_f32 v71, v66, v67
	global_store_dwordx4 v[84:85], v[68:71], off offset:256
	v_cvt_pk_bf16_f32 v60, v60, v61
	v_cvt_pk_bf16_f32 v61, v62, v63
	v_cvt_pk_bf16_f32 v62, v56, v57
	v_cvt_pk_bf16_f32 v63, v58, v59
	global_store_dwordx4 v[64:65], v[60:63], off
	v_cvt_pk_bf16_f32 v48, v48, v49
	v_cvt_pk_bf16_f32 v49, v50, v51
	v_cvt_pk_bf16_f32 v50, v40, v41
	v_add_u32_e32 v40, 0x90, v150
	v_ashrrev_i32_e32 v41, 31, v40
	v_lshlrev_b64 v[40:41], 12, v[40:41]
	v_cvt_pk_bf16_f32 v51, v42, v43
	global_store_dwordx4 v[64:65], v[48:51], off offset:256
	s_nop 1
	v_lshl_add_u64 v[48:49], v[148:149], 0, v[40:41]
	v_cvt_pk_bf16_f32 v40, v52, v53
	v_cvt_pk_bf16_f32 v41, v54, v55
	v_cvt_pk_bf16_f32 v42, v44, v45
	v_cvt_pk_bf16_f32 v43, v46, v47
	global_store_dwordx4 v[48:49], v[40:43], off
	v_cvt_pk_bf16_f32 v32, v32, v33
	v_cvt_pk_bf16_f32 v33, v34, v35
	v_cvt_pk_bf16_f32 v34, v24, v25
	v_add_u32_e32 v24, 0xa0, v150
	v_ashrrev_i32_e32 v25, 31, v24
	v_lshlrev_b64 v[24:25], 12, v[24:25]
	v_cvt_pk_bf16_f32 v35, v26, v27
	global_store_dwordx4 v[48:49], v[32:35], off offset:256
	s_nop 1
	v_lshl_add_u64 v[32:33], v[148:149], 0, v[24:25]
	v_cvt_pk_bf16_f32 v24, v36, v37
	v_cvt_pk_bf16_f32 v25, v38, v39
	v_cvt_pk_bf16_f32 v26, v28, v29
	v_cvt_pk_bf16_f32 v27, v30, v31
	global_store_dwordx4 v[32:33], v[24:27], off
	v_cvt_pk_bf16_f32 v16, v16, v17
	v_cvt_pk_bf16_f32 v17, v18, v19
	v_cvt_pk_bf16_f32 v18, v8, v9
	v_add_u32_e32 v8, 0xb0, v150
	v_ashrrev_i32_e32 v9, 31, v8
	v_lshlrev_b64 v[8:9], 12, v[8:9]
	v_cvt_pk_bf16_f32 v19, v10, v11
	global_store_dwordx4 v[32:33], v[16:19], off offset:256
	s_nop 1
	v_lshl_add_u64 v[16:17], v[148:149], 0, v[8:9]
	v_cvt_pk_bf16_f32 v8, v20, v21
	v_cvt_pk_bf16_f32 v9, v22, v23
	v_cvt_pk_bf16_f32 v10, v12, v13
	v_cvt_pk_bf16_f32 v11, v14, v15
	global_store_dwordx4 v[16:17], v[8:11], off
	v_cvt_pk_bf16_f32 v4, v4, v5
	v_cvt_pk_bf16_f32 v5, v6, v7
	v_cvt_pk_bf16_f32 v6, v0, v1
	v_cvt_pk_bf16_f32 v7, v2, v3
	global_store_dwordx4 v[16:17], v[4:7], off offset:256
	s_cbranch_vccz .LBB0_865
	s_waitcnt vmcnt(0)
	s_cmpk_gt_u32 s3, 0xff
	s_cbranch_scc1 .LBB0_876
	s_barrier

; __device__ void phase_peer(const Params& P, unsigned char* smem) {
;     ...
;         const int item = item0 + slot * (int)gridDim.x; if (item >= T / 32) break;
;         const int tok0 = item * 32;
;         unsigned short* ids = (unsigned short*)(smem + slot * 24576); float* gts = (float*)(smem + slot * 24576 + 8192);
;         {
;             const int h = wid;
; #pragma unroll 1
;             for (int p = 0; p < (((REPMASK >> 3) & 1) ? 4 : 2); ++p) {
;                 const int hp_ = h * 2 + (p & 1);
;                 const bf16_t* qp_ = QP + (size_t)(tok0 + l15) * D + hp_ * 128 + l4 * 8;
;     ...
;                         for (int q = 0; q < 16; ++q) R[q] = (unsigned)__shfl_xor((int)L[q], 16 << rnd);
.LBB0_958:
	s_mul_i32 s18, s42, s3
	s_add_i32 s18, s18, s75
	s_cmpk_gt_i32 s18, 0x3ff
	s_mov_b64 s[0:1], -1
	s_cbranch_scc1 .LBB0_957
	v_lshl_or_b32 v0, s18, 5, v106
	v_ashrrev_i32_e32 v1, 31, v0
	v_lshlrev_b64 v[0:1], 12, v[0:1]
	v_lshl_add_u64 v[40:41], v[50:51], 0, v[0:1]
	v_bfe_i32 v254, v144, 0, 1
	v_and_b32_e32 v254, 0xfffff040, v254
	v_add_u32_e32 v254, 0x800, v254
	v_ashrrev_i32_e32 v255, 31, v254
	v_lshl_add_u64 v[40:41], v[254:255], 0, v[40:41]
	v_and_b32_e32 v0, 64, v112
	v_add_u32_e32 v0, 64, v0
	v_xor_b32_e32 v1, 16, v112
	v_cmp_lt_i32_e32 vcc, v1, v0
	s_mov_b32 s76, 0
	s_mov_b64 s[46:47], -1
	v_cndmask_b32_e32 v1, v112, v1, vcc
	v_lshlrev_b32_e32 v42, 2, v1
	v_xor_b32_e32 v1, 32, v112
	v_cmp_lt_i32_e32 vcc, v1, v0
	s_nop 1
	v_cndmask_b32_e32 v0, v112, v1, vcc
	v_lshlrev_b32_e32 v43, 2, v0
	s_branch .LBB0_961

; __device__ __forceinline__ f32x4 mfma16(bf16x8 a, bf16x8 b, f32x4 c) { return __builtin_amdgcn_mfma_f32_16x16x32_bf16(a, b, c, 0, 0, 0); }
; __device__ __forceinline__ unsigned fkey(float f) { const unsigned u = __float_as_uint(f); return u ^ ((unsigned)((int)u >> 31) | 0x80000000u); }
; __device__ void phase_peer(const Params& P, unsigned char* smem) {
;     ...
;                 const int hp_ = h * 2 + (p & 1);
;                 const bf16_t* qp_ = QP + (size_t)(tok0 + l15) * D + hp_ * 128 + l4 * 8;
;                 const bf16_t* kp_ = SKB + ((size_t)hp_ * 128 + l15) * 128 + l4 * 8;
;                 f32x4 acc[2][8];
; #pragma unroll
;                 for (int th = 0; th < 2; ++th)
; #pragma unroll
;                     for (int tn = 0; tn < 8; ++tn) acc[th][tn] = (f32x4){0.f, 0.f, 0.f, 0.f};
; #pragma unroll
;                 for (int ks = 0; ks < 4; ++ks) {
;                     bf16x8 qf[2], kf[8];
; #pragma unroll
;                     for (int th = 0; th < 2; ++th) qf[th] = *(const bf16x8*)(qp_ + (size_t)th * 16 * D + ks * 32);
; #pragma unroll
;                     for (int tn = 0; tn < 8; ++tn) kf[tn] = *(const bf16x8*)(kp_ + tn * 16 * 128 + ks * 32);
; #pragma unroll
;                     for (int th = 0; th < 2; ++th)
; #pragma unroll
;                         for (int tn = 0; tn < 8; ++tn) acc[th][tn] = mfma16(kf[tn], qf[th], acc[th][tn]);
;                 }
; #pragma unroll
;                 for (int th = 0; th < 2; ++th) {
;                     unsigned S32[32];
; #pragma unroll
;                     for (int tn = 0; tn < 8; ++tn)
; #pragma unroll
;                         for (int jj = 0; jj < 4; ++jj) S32[tn * 4 + jj] = (fkey(acc[th][tn][jj]) & ~127u) | (unsigned)(tn * 16 + l4 * 4 + jj);
.LBB0_961:
	v_or_b32_e32 v0, s76, v108
	v_lshlrev_b32_e32 v48, 8, v0
	v_lshl_add_u64 v[216:217], v[40:41], 0, v[48:49]
	v_lshl_or_b32 v48, v0, 15, v154
	v_add_co_u32_e32 v244, vcc, 0x10000, v216
	v_lshl_add_u64 v[208:209], v[52:53], 0, v[48:49]
	s_nop 0
	v_addc_co_u32_e32 v245, vcc, 0, v217, vcc
	v_add_co_u32_e32 v204, vcc, s29, v208
	s_mov_b64 s[18:19], vcc
	v_add_co_u32_e32 v228, vcc, s49, v208
	global_load_dwordx4 v[0:3], v[216:217], off offset:-2048
	s_nop 0
	v_addc_co_u32_e32 v229, vcc, 0, v209, vcc
	v_add_co_u32_e32 v236, vcc, s52, v208
	s_mov_b64 s[0:1], vcc
	v_add_co_u32_e32 v212, vcc, s53, v208
	s_mov_b64 s[20:21], vcc
	v_add_co_u32_e32 v220, vcc, s54, v208
	s_mov_b64 s[22:23], vcc
	v_add_co_u32_e32 v246, vcc, s55, v208
	s_mov_b64 s[24:25], vcc
	v_add_co_u32_e32 v232, vcc, s56, v208
	s_waitcnt lgkmcnt(14)
	global_load_dwordx4 v[4:7], v[244:245], off offset:-2048
	s_waitcnt lgkmcnt(11)
	global_load_dwordx4 v[8:11], v[208:209], off
	v_addc_co_u32_e32 v233, vcc, 0, v209, vcc
	v_addc_co_u32_e64 v213, vcc, 0, v209, s[20:21]
	v_addc_co_u32_e64 v247, vcc, 0, v209, s[24:25]
	v_addc_co_u32_e64 v205, vcc, 0, v209, s[18:19]
	s_waitcnt lgkmcnt(7)
	global_load_dwordx4 v[12:15], v[228:229], off offset:-4096
	global_load_dwordx4 v[16:19], v[216:217], off offset:-1920
	s_waitcnt lgkmcnt(3)
	global_load_dwordx4 v[20:23], v[208:209], off offset:64
	s_waitcnt lgkmcnt(1)
	global_load_dwordx4 v[24:27], v[244:245], off offset:-1920
	s_waitcnt lgkmcnt(0)
	global_load_dwordx4 v[28:31], v[232:233], off offset:192
	global_load_dwordx4 v[44:47], v[228:229], off
	global_load_dwordx4 v[66:69], v[228:229], off offset:64
	global_load_dwordx4 v[74:77], v[212:213], off offset:-4096
	global_load_dwordx4 v[78:81], v[212:213], off
	global_load_dwordx4 v[90:93], v[246:247], off offset:-4096
	global_load_dwordx4 v[94:97], v[246:247], off
	global_load_dwordx4 v[98:101], v[212:213], off offset:192
	global_load_dwordx4 v[168:171], v[204:205], off offset:64
	global_load_dwordx4 v[172:175], v[232:233], off
	v_addc_co_u32_e64 v237, vcc, 0, v209, s[0:1]
	v_addc_co_u32_e64 v221, vcc, 0, v209, s[22:23]
	global_load_dwordx4 v[160:163], v[246:247], off offset:64
	global_load_dwordx4 v[176:179], v[236:237], off offset:64
	global_load_dwordx4 v[180:183], v[204:205], off offset:128
	global_load_dwordx4 v[184:187], v[212:213], off offset:64
	global_load_dwordx4 v[188:191], v[220:221], off offset:64
	global_load_dwordx4 v[192:195], v[220:221], off offset:192
	global_load_dwordx4 v[196:199], v[232:233], off offset:64
	s_lshl_b32 s18, s76, 4
	s_waitcnt vmcnt(21)
	v_mfma_f32_16x16x32_bf16 v[32:35], v[8:11], v[0:3], 0
	v_mfma_f32_16x16x32_bf16 v[8:11], v[8:11], v[4:7], 0
	s_waitcnt vmcnt(20)
	v_mfma_f32_16x16x32_bf16 v[36:39], v[12:15], v[0:3], 0
	s_waitcnt vmcnt(15)
	v_mfma_f32_16x16x32_bf16 v[70:73], v[44:47], v[0:3], 0
	v_mfma_f32_16x16x32_bf16 v[12:15], v[12:15], v[4:7], 0
	v_mfma_f32_16x16x32_bf16 v[44:47], v[44:47], v[4:7], 0
	s_waitcnt vmcnt(13)
	v_mfma_f32_16x16x32_bf16 v[82:85], v[74:77], v[0:3], 0
	s_waitcnt vmcnt(12)
	v_mfma_f32_16x16x32_bf16 v[86:89], v[78:81], v[0:3], 0
	v_mfma_f32_16x16x32_bf16 v[74:77], v[74:77], v[4:7], 0
	v_mfma_f32_16x16x32_bf16 v[78:81], v[78:81], v[4:7], 0
	s_waitcnt vmcnt(11)
	v_mfma_f32_16x16x32_bf16 v[102:105], v[90:93], v[0:3], 0
	s_waitcnt vmcnt(10)
	v_mfma_f32_16x16x32_bf16 v[164:167], v[94:97], v[0:3], 0
	v_mfma_f32_16x16x32_bf16 v[90:93], v[90:93], v[4:7], 0
	v_mfma_f32_16x16x32_bf16 v[94:97], v[94:97], v[4:7], 0
	s_waitcnt vmcnt(7)
	v_mfma_f32_16x16x32_bf16 v[0:3], v[172:175], v[0:3], 0
	v_mfma_f32_16x16x32_bf16 v[4:7], v[172:175], v[4:7], 0
	global_load_dwordx4 v[172:175], v[208:209], off offset:128
	global_load_dwordx4 v[200:203], v[216:217], off offset:2048
	s_nop 0
	global_load_dwordx4 v[204:207], v[204:205], off offset:192
	s_nop 0
	global_load_dwordx4 v[208:211], v[208:209], off offset:192
	s_nop 0
	global_load_dwordx4 v[212:215], v[212:213], off offset:128
	s_nop 0
	global_load_dwordx4 v[216:219], v[216:217], off offset:2176
	s_nop 0
	global_load_dwordx4 v[220:223], v[220:221], off offset:128
	v_mfma_f32_16x16x32_bf16 v[32:35], v[20:23], v[16:19], v[32:35]
	global_load_dwordx4 v[224:227], v[228:229], off offset:128
	s_nop 0
	global_load_dwordx4 v[228:231], v[228:229], off offset:192
	s_nop 0
	global_load_dwordx4 v[232:235], v[232:233], off offset:128
	v_mfma_f32_16x16x32_bf16 v[36:39], v[168:171], v[16:19], v[36:39]
	v_mfma_f32_16x16x32_bf16 v[70:73], v[66:69], v[16:19], v[70:73]
	s_waitcnt vmcnt(15)
	v_mfma_f32_16x16x32_bf16 v[82:85], v[176:179], v[16:19], v[82:85]
	s_waitcnt vmcnt(13)
	v_mfma_f32_16x16x32_bf16 v[86:89], v[184:187], v[16:19], v[86:89]
	s_waitcnt vmcnt(12)
	v_mfma_f32_16x16x32_bf16 v[102:105], v[188:191], v[16:19], v[102:105]
	v_mfma_f32_16x16x32_bf16 v[164:167], v[160:163], v[16:19], v[164:167]
	s_waitcnt vmcnt(10)
	v_mfma_f32_16x16x32_bf16 v[0:3], v[196:199], v[16:19], v[0:3]
	global_load_dwordx4 v[16:19], v[236:237], off offset:128
	v_mfma_f32_16x16x32_bf16 v[12:15], v[168:171], v[24:27], v[12:15]
	global_load_dwordx4 v[168:171], v[244:245], off offset:2048
	s_nop 0
	global_load_dwordx4 v[236:239], v[236:237], off offset:192
	v_mfma_f32_16x16x32_bf16 v[8:11], v[20:23], v[24:27], v[8:11]
	global_load_dwordx4 v[20:23], v[246:247], off offset:128
	s_waitcnt vmcnt(12)
	v_mfma_f32_16x16x32_bf16 v[32:35], v[172:175], v[200:203], v[32:35]
	s_waitcnt vmcnt(8)
	v_mfma_f32_16x16x32_bf16 v[240:243], v[208:211], v[216:219], v[32:35]
	s_nop 5
	global_load_dwordx4 v[32:35], v[244:245], off offset:2176
	s_nop 0
	global_load_dwordx4 v[244:247], v[246:247], off offset:192
	v_ashrrev_i32_e32 v48, 31, v240
	v_mfma_f32_16x16x32_bf16 v[36:39], v[180:183], v[200:203], v[36:39]
	v_bitop3_b32 v48, v48, v240, s57 bitop3:0x36
	v_ashrrev_i32_e32 v240, 31, v241
	v_and_or_b32 v48, v48, s58, v109
	v_mfma_f32_16x16x32_bf16 v[36:39], v[204:207], v[216:219], v[36:39]
	s_waitcnt vmcnt(8)
; __device__ __forceinline__ f32x4 mfma16(bf16x8 a, bf16x8 b, f32x4 c) { return __builtin_amdgcn_mfma_f32_16x16x32_bf16(a, b, c, 0, 0, 0); }
; __device__ __forceinline__ unsigned fkey(float f) { const unsigned u = __float_as_uint(f); return u ^ ((unsigned)((int)u >> 31) | 0x80000000u); }
; __device__ void phase_peer(const Params& P, unsigned char* smem) {
;     ...
;                         for (int tn = 0; tn < 8; ++tn) acc[th][tn] = mfma16(kf[tn], qf[th], acc[th][tn]);
;                 }
; #pragma unroll
;                 for (int th = 0; th < 2; ++th) {
;                     unsigned S32[32];
; #pragma unroll
;                     for (int tn = 0; tn < 8; ++tn)
; #pragma unroll
;                         for (int jj = 0; jj < 4; ++jj) S32[tn * 4 + jj] = (fkey(acc[th][tn][jj]) & ~127u) | (unsigned)(tn * 16 + l4 * 4 + jj);
	v_mfma_f32_16x16x32_bf16 v[70:73], v[224:227], v[200:203], v[70:73]
	v_mfma_f32_16x16x32_bf16 v[44:47], v[66:69], v[24:27], v[44:47]
	v_mfma_f32_16x16x32_bf16 v[66:69], v[176:179], v[24:27], v[74:77]
	s_nop 3
	v_ashrrev_i32_e32 v179, 31, v36
	v_bitop3_b32 v36, v179, v36, s57 bitop3:0x36
	v_and_or_b32 v179, v36, s58, v118
	v_bitop3_b32 v74, v240, v241, s57 bitop3:0x36
	v_and_or_b32 v176, v74, s58, v115
	v_ashrrev_i32_e32 v74, 31, v242
	v_bitop3_b32 v74, v74, v242, s57 bitop3:0x36
	s_waitcnt vmcnt(7)
	v_mfma_f32_16x16x32_bf16 v[70:73], v[228:231], v[216:219], v[70:73]
	v_and_or_b32 v177, v74, s58, v116
	v_ashrrev_i32_e32 v74, 31, v243
	v_ashrrev_i32_e32 v36, 31, v37
	v_bitop3_b32 v74, v74, v243, s57 bitop3:0x36
	v_bitop3_b32 v36, v36, v37, s57 bitop3:0x36
	v_and_or_b32 v178, v74, s58, v117
	v_mfma_f32_16x16x32_bf16 v[74:77], v[184:187], v[24:27], v[78:81]
	v_mfma_f32_16x16x32_bf16 v[78:81], v[188:191], v[24:27], v[90:93]
	s_nop 2
	v_and_or_b32 v90, v36, s58, v119
	v_ashrrev_i32_e32 v36, 31, v38
	v_bitop3_b32 v36, v36, v38, s57 bitop3:0x36
	v_ashrrev_i32_e32 v93, 31, v70
	v_and_or_b32 v91, v36, s58, v120
	v_ashrrev_i32_e32 v36, 31, v39
	v_bitop3_b32 v70, v93, v70, s57 bitop3:0x36
	v_bitop3_b32 v36, v36, v39, s57 bitop3:0x36
	v_and_or_b32 v93, v70, s58, v122
	v_ashrrev_i32_e32 v70, 31, v71
	v_and_or_b32 v92, v36, s58, v121
	v_mfma_f32_16x16x32_bf16 v[36:39], v[160:163], v[24:27], v[94:97]
	v_mfma_f32_16x16x32_bf16 v[4:7], v[196:199], v[24:27], v[4:7]
	v_bitop3_b32 v24, v70, v71, s57 bitop3:0x36
	s_nop 0
	v_and_or_b32 v94, v24, s58, v123
	v_ashrrev_i32_e32 v70, 31, v72
	s_waitcnt vmcnt(5)
	v_mfma_f32_16x16x32_bf16 v[24:27], v[16:19], v[200:203], v[82:85]
	v_bitop3_b32 v70, v70, v72, s57 bitop3:0x36
	v_and_or_b32 v95, v70, s58, v124
	v_ashrrev_i32_e32 v70, 31, v73
	s_waitcnt vmcnt(3)
	v_mfma_f32_16x16x32_bf16 v[24:27], v[236:239], v[216:219], v[24:27]
	v_bitop3_b32 v70, v70, v73, s57 bitop3:0x36
	v_and_or_b32 v96, v70, s58, v125
	v_mfma_f32_16x16x32_bf16 v[70:73], v[212:215], v[200:203], v[86:89]
	v_mfma_f32_16x16x32_bf16 v[70:73], v[98:101], v[216:219], v[70:73]
	s_nop 3
	v_ashrrev_i32_e32 v82, 31, v24
	v_bitop3_b32 v24, v82, v24, s57 bitop3:0x36
	v_and_or_b32 v97, v24, s58, v126
	v_ashrrev_i32_e32 v24, 31, v25
	v_bitop3_b32 v24, v24, v25, s57 bitop3:0x36
	v_mfma_f32_16x16x32_bf16 v[82:85], v[220:223], v[200:203], v[102:105]
	s_nop 2
	v_and_or_b32 v102, v24, s58, v127
	v_ashrrev_i32_e32 v24, 31, v26
	v_bitop3_b32 v24, v24, v26, s57 bitop3:0x36
	v_and_or_b32 v103, v24, s58, v128
	v_ashrrev_i32_e32 v24, 31, v27
	v_bitop3_b32 v24, v24, v27, s57 bitop3:0x36
	v_and_or_b32 v104, v24, s58, v129
	v_ashrrev_i32_e32 v24, 31, v70
	v_bitop3_b32 v24, v24, v70, s57 bitop3:0x36
	v_and_or_b32 v105, v24, s58, v130
	v_ashrrev_i32_e32 v24, 31, v71
	v_bitop3_b32 v24, v24, v71, s57 bitop3:0x36
	v_and_or_b32 v160, v24, s58, v131
	v_ashrrev_i32_e32 v24, 31, v72
	v_bitop3_b32 v24, v24, v72, s57 bitop3:0x36
	v_and_or_b32 v161, v24, s58, v132
	v_mfma_f32_16x16x32_bf16 v[24:27], v[192:195], v[216:219], v[82:85]
	v_ashrrev_i32_e32 v70, 31, v73
	v_bitop3_b32 v70, v70, v73, s57 bitop3:0x36
	s_nop 0
	v_and_or_b32 v82, v70, s58, v133
	s_waitcnt vmcnt(2)
	v_mfma_f32_16x16x32_bf16 v[86:89], v[20:23], v[200:203], v[164:167]
	s_nop 1
	v_ashrrev_i32_e32 v70, 31, v24
	v_bitop3_b32 v24, v70, v24, s57 bitop3:0x36
	v_and_or_b32 v83, v24, s58, v134
	v_ashrrev_i32_e32 v24, 31, v25
	v_mfma_f32_16x16x32_bf16 v[66:69], v[16:19], v[168:171], v[66:69]
	v_bitop3_b32 v16, v24, v25, s57 bitop3:0x36
	v_and_or_b32 v84, v16, s58, v135
	v_ashrrev_i32_e32 v16, 31, v26
	v_bitop3_b32 v16, v16, v26, s57 bitop3:0x36
	v_and_or_b32 v85, v16, s58, v136
	s_waitcnt vmcnt(0)
	v_mfma_f32_16x16x32_bf16 v[16:19], v[244:247], v[216:219], v[86:89]
	v_ashrrev_i32_e32 v24, 31, v27
	v_bitop3_b32 v24, v24, v27, s57 bitop3:0x36
	v_mfma_f32_16x16x32_bf16 v[0:3], v[232:235], v[200:203], v[0:3]
	v_and_or_b32 v86, v24, s58, v137
	s_nop 3
	v_ashrrev_i32_e32 v24, 31, v16
	v_bitop3_b32 v16, v24, v16, s57 bitop3:0x36
	v_and_or_b32 v87, v16, s58, v138
	v_ashrrev_i32_e32 v16, 31, v17
	v_bitop3_b32 v16, v16, v17, s57 bitop3:0x36
	v_and_or_b32 v88, v16, s58, v139
	v_ashrrev_i32_e32 v16, 31, v18
	v_mfma_f32_16x16x32_bf16 v[0:3], v[28:31], v[216:219], v[0:3]
	v_mfma_f32_16x16x32_bf16 v[70:73], v[212:215], v[168:171], v[74:77]
	v_mfma_f32_16x16x32_bf16 v[74:77], v[220:223], v[168:171], v[78:81]
	v_mfma_f32_16x16x32_bf16 v[78:81], v[20:23], v[168:171], v[36:39]
	v_mfma_f32_16x16x32_bf16 v[36:39], v[232:235], v[168:171], v[4:7]
	s_nop 2
	v_bitop3_b32 v4, v16, v18, s57 bitop3:0x36
	v_and_or_b32 v89, v4, s58, v140
	v_ashrrev_i32_e32 v4, 31, v19
	v_bitop3_b32 v4, v4, v19, s57 bitop3:0x36
	v_and_or_b32 v162, v4, s58, v141
	v_ashrrev_i32_e32 v4, 31, v0
	v_bitop3_b32 v0, v4, v0, s57 bitop3:0x36
	v_mfma_f32_16x16x32_bf16 v[44:47], v[224:227], v[168:171], v[44:47]
	v_and_or_b32 v163, v0, s58, v142
	v_ashrrev_i32_e32 v0, 31, v1
	v_bitop3_b32 v0, v0, v1, s57 bitop3:0x36
	v_and_or_b32 v164, v0, s58, v143
	v_ashrrev_i32_e32 v0, 31, v2
	v_mfma_f32_16x16x32_bf16 v[8:11], v[172:175], v[168:171], v[8:11]
	v_bitop3_b32 v0, v0, v2, s57 bitop3:0x36
	v_mfma_f32_16x16x32_bf16 v[12:15], v[180:183], v[168:171], v[12:15]
	v_mfma_f32_16x16x32_bf16 v[16:19], v[228:231], v[32:35], v[44:47]
	s_nop 2
	v_and_or_b32 v44, v0, s58, v145
	v_ashrrev_i32_e32 v0, 31, v3
	v_bitop3_b32 v0, v0, v3, s57 bitop3:0x36
	v_and_or_b32 v45, v0, s58, v148
	v_mfma_f32_16x16x32_bf16 v[24:27], v[208:211], v[32:35], v[8:11]
	v_max_u32_e32 v46, v48, v176
	v_min_u32_e32 v47, v48, v176
	v_max_u32_e32 v48, v177, v178
	v_mfma_f32_16x16x32_bf16 v[20:23], v[204:207], v[32:35], v[12:15]
; __device__ __forceinline__ f32x4 mfma16(bf16x8 a, bf16x8 b, f32x4 c) { return __builtin_amdgcn_mfma_f32_16x16x32_bf16(a, b, c, 0, 0, 0); }
; __device__ void phase_peer(const Params& P, unsigned char* smem) {
;     ...
;                         for (int tn = 0; tn < 8; ++tn) acc[th][tn] = mfma16(kf[tn], qf[th], acc[th][tn]);
;     ...
;                     for (int k = 2; k <= 32; k <<= 1)
; #pragma unroll
;                         for (int j = k >> 1; j >= 1; j >>= 1)
; #pragma unroll
;                             for (int i = 0; i < 32; ++i) {
;                                 const int l = i ^ j;
;                                 if (l > i) {
;                                     const unsigned hi_ = max(S32[i], S32[l]), lo_ = min(S32[i], S32[l]);
;                                     if ((i & k) == 0) { S32[i] = hi_; S32[l] = lo_; } else { S32[i] = lo_; S32[l] = hi_; }
;                                 }
;                             }
	v_mfma_f32_16x16x32_bf16 v[12:15], v[236:239], v[32:35], v[66:69]
	v_mfma_f32_16x16x32_bf16 v[8:11], v[98:101], v[32:35], v[70:73]
	s_nop 1
	v_min_u32_e32 v66, v177, v178
	v_max_u32_e32 v67, v179, v90
	v_min_u32_e32 v68, v179, v90
	v_mfma_f32_16x16x32_bf16 v[4:7], v[192:195], v[32:35], v[74:77]
	v_max_u32_e32 v69, v91, v92
	v_min_u32_e32 v70, v91, v92
	v_max_u32_e32 v71, v93, v94
	v_mfma_f32_16x16x32_bf16 v[0:3], v[244:247], v[32:35], v[78:81]
	v_min_u32_e32 v72, v93, v94
	v_max_u32_e32 v73, v95, v96
	v_min_u32_e32 v74, v95, v96
	v_max_u32_e32 v75, v97, v102
	v_min_u32_e32 v76, v97, v102
	v_max_u32_e32 v77, v103, v104
	v_min_u32_e32 v78, v103, v104
	v_max_u32_e32 v79, v105, v160
	v_min_u32_e32 v80, v105, v160
	v_max_u32_e32 v81, v161, v82
	v_min_u32_e32 v82, v161, v82
	v_max_u32_e32 v90, v83, v84
	v_min_u32_e32 v83, v83, v84
	v_max_u32_e32 v84, v85, v86
	v_min_u32_e32 v85, v85, v86
	v_max_u32_e32 v86, v87, v88
	v_min_u32_e32 v87, v87, v88
	v_max_u32_e32 v88, v89, v162
	v_min_u32_e32 v89, v89, v162
	v_max_u32_e32 v91, v163, v164
	v_min_u32_e32 v92, v163, v164
	v_max_u32_e32 v93, v44, v45
	v_min_u32_e32 v44, v44, v45
	v_max_u32_e32 v45, v46, v66
	v_min_u32_e32 v46, v46, v66
	v_max_u32_e32 v66, v47, v48
	v_min_u32_e32 v47, v47, v48
	v_max_u32_e32 v48, v67, v70
	v_min_u32_e32 v67, v67, v70
	v_max_u32_e32 v70, v68, v69
	v_min_u32_e32 v68, v68, v69
	v_max_u32_e32 v69, v71, v74
	v_min_u32_e32 v71, v71, v74
	v_max_u32_e32 v74, v72, v73
	v_min_u32_e32 v72, v72, v73
	v_max_u32_e32 v73, v75, v78
	v_min_u32_e32 v75, v75, v78
	v_max_u32_e32 v78, v76, v77
	v_min_u32_e32 v76, v76, v77
	v_max_u32_e32 v77, v79, v82
	v_min_u32_e32 v79, v79, v82
	v_max_u32_e32 v82, v80, v81
	v_min_u32_e32 v80, v80, v81
	v_max_u32_e32 v81, v90, v85
	v_min_u32_e32 v85, v90, v85
	v_max_u32_e32 v90, v83, v84
	v_min_u32_e32 v83, v83, v84
	v_max_u32_e32 v84, v86, v89
	v_min_u32_e32 v86, v86, v89
	v_max_u32_e32 v89, v87, v88
	v_min_u32_e32 v87, v87, v88
	v_max_u32_e32 v88, v91, v44
	v_min_u32_e32 v44, v91, v44
	v_max_u32_e32 v91, v92, v93
	v_min_u32_e32 v92, v92, v93
	v_max_u32_e32 v93, v45, v66
	v_min_u32_e32 v45, v45, v66
	v_max_u32_e32 v66, v46, v47
	v_min_u32_e32 v46, v46, v47
	v_max_u32_e32 v47, v67, v68
	v_min_u32_e32 v67, v67, v68
	v_max_u32_e32 v68, v48, v70
	v_min_u32_e32 v48, v48, v70
	v_max_u32_e32 v70, v69, v74
	v_min_u32_e32 v69, v69, v74
	v_max_u32_e32 v74, v71, v72
	v_min_u32_e32 v71, v71, v72
	v_max_u32_e32 v72, v75, v76
	v_min_u32_e32 v75, v75, v76
	v_max_u32_e32 v76, v73, v78
	v_min_u32_e32 v73, v73, v78
	v_max_u32_e32 v78, v77, v82
	v_min_u32_e32 v77, v77, v82
	v_max_u32_e32 v82, v79, v80
	v_min_u32_e32 v79, v79, v80
	v_max_u32_e32 v80, v85, v83
	v_min_u32_e32 v83, v85, v83
	v_max_u32_e32 v85, v81, v90
	v_min_u32_e32 v81, v81, v90
	v_max_u32_e32 v90, v84, v89
	v_min_u32_e32 v84, v84, v89
	v_max_u32_e32 v89, v86, v87
	v_min_u32_e32 v86, v86, v87
	v_max_u32_e32 v87, v44, v92
	v_min_u32_e32 v44, v44, v92
	v_max_u32_e32 v92, v88, v91
	v_min_u32_e32 v88, v88, v91
	v_max_u32_e32 v91, v93, v67
	v_min_u32_e32 v67, v93, v67
	v_max_u32_e32 v93, v45, v47
	v_min_u32_e32 v45, v45, v47
	v_max_u32_e32 v47, v66, v48
	v_min_u32_e32 v48, v66, v48
	v_max_u32_e32 v66, v46, v68
	v_min_u32_e32 v46, v46, v68
	v_max_u32_e32 v68, v70, v75
	v_min_u32_e32 v70, v70, v75
	v_max_u32_e32 v75, v69, v72
	v_min_u32_e32 v69, v69, v72
	v_max_u32_e32 v72, v74, v73
	v_min_u32_e32 v73, v74, v73
	v_max_u32_e32 v74, v71, v76
	v_min_u32_e32 v71, v71, v76
	v_max_u32_e32 v76, v78, v83
	v_min_u32_e32 v78, v78, v83
	v_max_u32_e32 v83, v77, v80
	v_min_u32_e32 v77, v77, v80
	v_max_u32_e32 v80, v82, v81
	v_min_u32_e32 v81, v82, v81
	v_max_u32_e32 v82, v79, v85
	v_min_u32_e32 v79, v79, v85
	v_max_u32_e32 v85, v90, v44
	v_min_u32_e32 v44, v90, v44
	v_max_u32_e32 v90, v84, v87
	v_min_u32_e32 v84, v84, v87
	v_max_u32_e32 v87, v89, v88
	v_min_u32_e32 v88, v89, v88
	v_max_u32_e32 v89, v86, v92
	v_min_u32_e32 v86, v86, v92
	v_max_u32_e32 v92, v91, v47
	v_min_u32_e32 v47, v91, v47
	v_max_u32_e32 v91, v93, v66
	v_min_u32_e32 v66, v93, v66
	v_max_u32_e32 v93, v67, v48
	v_min_u32_e32 v48, v67, v48
	v_max_u32_e32 v67, v45, v46
	v_min_u32_e32 v45, v45, v46
	v_max_u32_e32 v46, v70, v73
	v_min_u32_e32 v70, v70, v73
	v_max_u32_e32 v73, v69, v71
	v_min_u32_e32 v69, v69, v71
	v_max_u32_e32 v71, v68, v72
	v_min_u32_e32 v68, v68, v72
	v_max_u32_e32 v72, v75, v74
	v_min_u32_e32 v74, v75, v74
	v_max_u32_e32 v75, v76, v80
	v_min_u32_e32 v76, v76, v80
	v_max_u32_e32 v80, v83, v82
	v_min_u32_e32 v82, v83, v82
	v_max_u32_e32 v83, v78, v81
	v_min_u32_e32 v78, v78, v81
	v_max_u32_e32 v81, v77, v79
	v_min_u32_e32 v77, v77, v79
	v_max_u32_e32 v79, v44, v88
	v_min_u32_e32 v44, v44, v88
	v_max_u32_e32 v88, v84, v86
	v_min_u32_e32 v84, v84, v86
	v_max_u32_e32 v86, v85, v87
	v_min_u32_e32 v85, v85, v87
	v_max_u32_e32 v87, v90, v89
	v_min_u32_e32 v89, v90, v89
	v_max_u32_e32 v90, v92, v91
	v_min_u32_e32 v91, v92, v91
	v_max_u32_e32 v92, v47, v66
	v_min_u32_e32 v47, v47, v66
	v_max_u32_e32 v66, v93, v67
	v_min_u32_e32 v67, v93, v67
	v_max_u32_e32 v93, v48, v45
	v_min_u32_e32 v45, v48, v45
	v_max_u32_e32 v48, v70, v69
	v_min_u32_e32 v69, v70, v69
	v_max_u32_e32 v70, v46, v73
	v_min_u32_e32 v46, v46, v73
	v_max_u32_e32 v73, v68, v74
	v_min_u32_e32 v68, v68, v74
	v_max_u32_e32 v74, v71, v72
	v_min_u32_e32 v71, v71, v72
	v_max_u32_e32 v72, v75, v80
	v_min_u32_e32 v75, v75, v80
	v_max_u32_e32 v80, v76, v82
	v_min_u32_e32 v76, v76, v82
	v_max_u32_e32 v82, v83, v81
	v_min_u32_e32 v81, v83, v81
	v_max_u32_e32 v83, v78, v77
	v_min_u32_e32 v77, v78, v77
	v_max_u32_e32 v78, v44, v84
	v_min_u32_e32 v44, v44, v84
	v_max_u32_e32 v84, v79, v88
; __device__ void phase_peer(const Params& P, unsigned char* smem) {
;     ...
;                     for (int k = 2; k <= 32; k <<= 1)
; #pragma unroll
;                         for (int j = k >> 1; j >= 1; j >>= 1)
; #pragma unroll
;                             for (int i = 0; i < 32; ++i) {
;                                 const int l = i ^ j;
;                                 if (l > i) {
;                                     const unsigned hi_ = max(S32[i], S32[l]), lo_ = min(S32[i], S32[l]);
;                                     if ((i & k) == 0) { S32[i] = hi_; S32[l] = lo_; } else { S32[i] = lo_; S32[l] = hi_; }
;                                 }
;                             }
;                     unsigned L[16];
; #pragma unroll
;                     for (int q = 0; q < 16; ++q) L[q] = S32[q];
; #pragma unroll
;                     for (int rnd = 0; rnd < 2; ++rnd) {
;                         unsigned R[16];
; #pragma unroll
;                         for (int q = 0; q < 16; ++q) R[q] = (unsigned)__shfl_xor((int)L[q], 16 << rnd);
	v_min_u32_e32 v79, v79, v88
	v_max_u32_e32 v88, v85, v89
	v_min_u32_e32 v85, v85, v89
	v_max_u32_e32 v89, v86, v87
	v_min_u32_e32 v86, v86, v87
	v_max_u32_e32 v87, v90, v69
	v_min_u32_e32 v69, v90, v69
	v_max_u32_e32 v90, v91, v48
	v_min_u32_e32 v48, v91, v48
	v_max_u32_e32 v91, v92, v46
	v_min_u32_e32 v46, v92, v46
	v_max_u32_e32 v92, v47, v70
	v_min_u32_e32 v47, v47, v70
	v_max_u32_e32 v70, v66, v68
	v_min_u32_e32 v66, v66, v68
	v_max_u32_e32 v68, v67, v73
	v_min_u32_e32 v67, v67, v73
	v_max_u32_e32 v73, v93, v71
	v_min_u32_e32 v71, v93, v71
	v_max_u32_e32 v93, v45, v74
	v_min_u32_e32 v45, v45, v74
	v_max_u32_e32 v74, v72, v44
	v_min_u32_e32 v44, v72, v44
	v_max_u32_e32 v72, v75, v78
	v_min_u32_e32 v75, v75, v78
	v_max_u32_e32 v78, v80, v79
	v_min_u32_e32 v79, v80, v79
	v_max_u32_e32 v80, v76, v84
	v_min_u32_e32 v76, v76, v84
	v_max_u32_e32 v84, v82, v85
	v_min_u32_e32 v82, v82, v85
	v_max_u32_e32 v85, v81, v88
	v_min_u32_e32 v81, v81, v88
	v_max_u32_e32 v88, v83, v86
	v_min_u32_e32 v83, v83, v86
	v_max_u32_e32 v86, v77, v89
	v_min_u32_e32 v77, v77, v89
	v_max_u32_e32 v89, v87, v70
	v_min_u32_e32 v70, v87, v70
	v_max_u32_e32 v87, v90, v68
	v_min_u32_e32 v68, v90, v68
	v_max_u32_e32 v90, v91, v73
	v_min_u32_e32 v73, v91, v73
	v_max_u32_e32 v91, v92, v93
	v_min_u32_e32 v92, v92, v93
	v_max_u32_e32 v93, v69, v66
	v_min_u32_e32 v66, v69, v66
	v_max_u32_e32 v69, v48, v67
	v_min_u32_e32 v48, v48, v67
	v_max_u32_e32 v67, v46, v71
	v_min_u32_e32 v46, v46, v71
	v_max_u32_e32 v71, v47, v45
	v_min_u32_e32 v45, v47, v45
	v_max_u32_e32 v47, v44, v82
	v_min_u32_e32 v44, v44, v82
	v_max_u32_e32 v82, v75, v81
	v_min_u32_e32 v75, v75, v81
	v_max_u32_e32 v81, v79, v83
	v_min_u32_e32 v79, v79, v83
	v_max_u32_e32 v83, v76, v77
	v_min_u32_e32 v76, v76, v77
	v_max_u32_e32 v77, v74, v84
	v_min_u32_e32 v74, v74, v84
	v_max_u32_e32 v84, v72, v85
	v_min_u32_e32 v72, v72, v85
	v_max_u32_e32 v85, v78, v88
	v_min_u32_e32 v78, v78, v88
	v_max_u32_e32 v88, v80, v86
	v_min_u32_e32 v80, v80, v86
	v_max_u32_e32 v86, v89, v90
	v_min_u32_e32 v89, v89, v90
	v_max_u32_e32 v90, v87, v91
	v_min_u32_e32 v87, v87, v91
	v_max_u32_e32 v91, v70, v73
	v_min_u32_e32 v70, v70, v73
	v_max_u32_e32 v73, v68, v92
	v_min_u32_e32 v68, v68, v92
	v_max_u32_e32 v92, v93, v67
	v_min_u32_e32 v67, v93, v67
	v_max_u32_e32 v93, v69, v71
	v_min_u32_e32 v69, v69, v71
	v_max_u32_e32 v71, v66, v46
	v_min_u32_e32 v46, v66, v46
	v_max_u32_e32 v66, v48, v45
	v_min_u32_e32 v45, v48, v45
	v_max_u32_e32 v48, v44, v79
	v_min_u32_e32 v44, v44, v79
	v_max_u32_e32 v79, v75, v76
	v_min_u32_e32 v75, v75, v76
	v_max_u32_e32 v76, v47, v81
	v_min_u32_e32 v47, v47, v81
	v_max_u32_e32 v81, v82, v83
	v_min_u32_e32 v82, v82, v83
	v_max_u32_e32 v83, v74, v78
	v_min_u32_e32 v74, v74, v78
	v_max_u32_e32 v78, v72, v80
	v_min_u32_e32 v72, v72, v80
	v_max_u32_e32 v80, v77, v85
	v_min_u32_e32 v77, v77, v85
	v_max_u32_e32 v85, v84, v88
	v_min_u32_e32 v84, v84, v88
	v_min_u32_e32 v88, v86, v90
	v_min_u32_e32 v94, v89, v87
	v_min_u32_e32 v95, v91, v73
	v_min_u32_e32 v96, v70, v68
	v_min_u32_e32 v97, v92, v93
	v_min_u32_e32 v98, v67, v69
	v_min_u32_e32 v99, v71, v66
	v_min_u32_e32 v100, v46, v45
	v_min_u32_e32 v101, v44, v75
	v_min_u32_e32 v102, v48, v79
	v_min_u32_e32 v103, v47, v82
	v_min_u32_e32 v104, v76, v81
	v_min_u32_e32 v105, v74, v72
	v_min_u32_e32 v160, v83, v78
	v_min_u32_e32 v161, v77, v84
	v_min_u32_e32 v162, v80, v85
	v_max3_u32 v86, v86, v90, v101
	v_max3_u32 v44, v88, v44, v75
	v_max3_u32 v75, v89, v87, v102
	v_max3_u32 v48, v94, v48, v79
	v_max3_u32 v73, v91, v73, v103
	v_max3_u32 v47, v95, v47, v82
	v_max3_u32 v68, v70, v68, v104
	v_max3_u32 v70, v96, v76, v81
	v_max3_u32 v76, v92, v93, v105
	v_max3_u32 v72, v97, v74, v72
	v_max3_u32 v67, v67, v69, v160
	v_max3_u32 v69, v98, v83, v78
	v_max3_u32 v66, v71, v66, v161
	v_max3_u32 v71, v99, v77, v84
	v_max3_u32 v45, v46, v45, v162
	v_max3_u32 v46, v100, v80, v85
	v_max_u32_e32 v74, v86, v76
	v_min_u32_e32 v76, v86, v76
	v_max_u32_e32 v77, v44, v72
	v_min_u32_e32 v44, v44, v72
	v_max_u32_e32 v72, v75, v67
	v_min_u32_e32 v67, v75, v67
	v_max_u32_e32 v75, v48, v69
	v_min_u32_e32 v48, v48, v69
	v_max_u32_e32 v69, v73, v66
	v_min_u32_e32 v66, v73, v66
	v_max_u32_e32 v73, v47, v71
	v_min_u32_e32 v47, v47, v71
	v_max_u32_e32 v71, v68, v45
	v_min_u32_e32 v45, v68, v45
	v_max_u32_e32 v68, v70, v46
	v_min_u32_e32 v46, v70, v46
	v_max_u32_e32 v70, v74, v69
	v_min_u32_e32 v69, v74, v69
	v_max_u32_e32 v74, v77, v73
	v_min_u32_e32 v73, v77, v73
	v_max_u32_e32 v77, v72, v71
	v_min_u32_e32 v71, v72, v71
	v_max_u32_e32 v72, v75, v68
	v_min_u32_e32 v68, v75, v68
	v_max_u32_e32 v75, v76, v66
	v_min_u32_e32 v66, v76, v66
	v_max_u32_e32 v76, v44, v47
	v_min_u32_e32 v44, v44, v47
	v_max_u32_e32 v47, v67, v45
	v_min_u32_e32 v45, v67, v45
	v_max_u32_e32 v67, v48, v46
	v_min_u32_e32 v46, v48, v46
	v_max_u32_e32 v48, v70, v77
	v_min_u32_e32 v70, v70, v77
	v_max_u32_e32 v77, v74, v72
	v_min_u32_e32 v72, v74, v72
	v_max_u32_e32 v74, v69, v71
	v_min_u32_e32 v69, v69, v71
	v_max_u32_e32 v71, v73, v68
	v_min_u32_e32 v68, v73, v68
	v_max_u32_e32 v73, v75, v47
	v_min_u32_e32 v47, v75, v47
	v_max_u32_e32 v75, v76, v67
	v_min_u32_e32 v67, v76, v67
	v_max_u32_e32 v76, v66, v45
	v_min_u32_e32 v45, v66, v45
	v_max_u32_e32 v66, v44, v46
	v_min_u32_e32 v44, v44, v46
	v_max_u32_e32 v46, v48, v77
	v_min_u32_e32 v48, v48, v77
	v_max_u32_e32 v77, v70, v72
	v_min_u32_e32 v70, v70, v72
	v_max_u32_e32 v72, v74, v71
	v_min_u32_e32 v71, v74, v71
	v_max_u32_e32 v74, v69, v68
	v_min_u32_e32 v68, v69, v68
	v_max_u32_e32 v69, v73, v75
	v_min_u32_e32 v73, v73, v75
	v_max_u32_e32 v75, v47, v67
	v_min_u32_e32 v47, v47, v67
	v_max_u32_e32 v67, v76, v66
	v_min_u32_e32 v66, v76, v66
	v_max_u32_e32 v76, v45, v44
	v_min_u32_e32 v44, v45, v44
	ds_bpermute_b32 v45, v42, v46
	ds_bpermute_b32 v78, v42, v48
	ds_bpermute_b32 v79, v42, v77
	ds_bpermute_b32 v80, v42, v70
	ds_bpermute_b32 v81, v42, v72
	ds_bpermute_b32 v82, v42, v71
	ds_bpermute_b32 v83, v42, v74
	ds_bpermute_b32 v84, v42, v68
	ds_bpermute_b32 v85, v42, v69
	ds_bpermute_b32 v86, v42, v73
	ds_bpermute_b32 v87, v42, v75
	ds_bpermute_b32 v88, v42, v76
	ds_bpermute_b32 v89, v42, v66
	ds_bpermute_b32 v90, v42, v67
	ds_bpermute_b32 v91, v42, v47
	ds_bpermute_b32 v92, v42, v44
	s_waitcnt lgkmcnt(4)
; __device__ void phase_peer(const Params& P, unsigned char* smem) {
;     ...
;                         for (int q = 0; q < 16; ++q) R[q] = (unsigned)__shfl_xor((int)L[q], 16 << rnd);
; #pragma unroll
;                         for (int q = 0; q < 16; ++q) L[q] = max(L[q], R[15 - q]);
; #pragma unroll
;                         for (int d = 8; d >= 1; d >>= 1)
; #pragma unroll
;                             for (int q = 0; q < 16; ++q)
;                                 if ((q & d) == 0) { const unsigned hi_ = max(L[q], L[q + d]), lo_ = min(L[q], L[q + d]); L[q] = hi_; L[q + d] = lo_; }
;                     }
;                     if (l4 == 0) {
	v_max_u32_e32 v48, v48, v88
	s_waitcnt lgkmcnt(3)
	v_max_u32_e32 v77, v77, v89
	s_waitcnt lgkmcnt(2)
	v_max_u32_e32 v70, v70, v90
	s_waitcnt lgkmcnt(1)
	v_max_u32_e32 v72, v72, v91
	v_max_u32_e32 v71, v71, v87
	v_max_u32_e32 v74, v74, v86
	v_max_u32_e32 v68, v68, v85
	v_max_u32_e32 v73, v73, v83
	v_max_u32_e32 v75, v75, v82
	v_max_u32_e32 v47, v47, v81
	v_max_u32_e32 v67, v67, v80
	v_max_u32_e32 v66, v66, v79
	v_max_u32_e32 v76, v76, v78
	v_max_u32_e32 v44, v44, v45
	v_max_u32_e32 v45, v69, v84
	s_waitcnt lgkmcnt(0)
	v_max_u32_e32 v46, v46, v92
	v_max_u32_e32 v69, v46, v45
	v_min_u32_e32 v45, v46, v45
	v_max_u32_e32 v46, v48, v73
	v_min_u32_e32 v48, v48, v73
	v_max_u32_e32 v73, v77, v75
	v_min_u32_e32 v75, v77, v75
	v_max_u32_e32 v77, v70, v47
	v_min_u32_e32 v47, v70, v47
	v_max_u32_e32 v70, v72, v67
	v_min_u32_e32 v67, v72, v67
	v_max_u32_e32 v72, v71, v66
	v_min_u32_e32 v66, v71, v66
	v_max_u32_e32 v71, v74, v76
	v_min_u32_e32 v74, v74, v76
	v_max_u32_e32 v76, v68, v44
	v_min_u32_e32 v44, v68, v44
	v_max_u32_e32 v68, v69, v70
	v_min_u32_e32 v69, v69, v70
	v_max_u32_e32 v70, v46, v72
	v_min_u32_e32 v46, v46, v72
	v_max_u32_e32 v72, v73, v71
	v_min_u32_e32 v71, v73, v71
	v_max_u32_e32 v73, v77, v76
	v_min_u32_e32 v76, v77, v76
	v_max_u32_e32 v77, v45, v67
	v_min_u32_e32 v45, v45, v67
	v_max_u32_e32 v67, v48, v66
	v_min_u32_e32 v48, v48, v66
	v_max_u32_e32 v66, v75, v74
	v_min_u32_e32 v74, v75, v74
	v_max_u32_e32 v75, v47, v44
	v_min_u32_e32 v44, v47, v44
	v_max_u32_e32 v47, v68, v72
	v_min_u32_e32 v68, v68, v72
	v_max_u32_e32 v72, v70, v73
	v_min_u32_e32 v73, v70, v73
	v_max_u32_e32 v78, v69, v71
	v_min_u32_e32 v69, v69, v71
	v_max_u32_e32 v71, v46, v76
	v_min_u32_e32 v79, v46, v76
	v_max_u32_e32 v80, v77, v66
	v_min_u32_e32 v66, v77, v66
	v_max_u32_e32 v77, v67, v75
	v_min_u32_e32 v67, v67, v75
	v_max_u32_e32 v81, v45, v74
	v_min_u32_e32 v74, v45, v74
	v_max_u32_e32 v84, v48, v44
	v_min_u32_e32 v85, v48, v44
	v_max_u32_e32 v75, v47, v72
	v_min_u32_e32 v46, v47, v72
	v_max_u32_e32 v70, v68, v73
	v_min_u32_e32 v44, v68, v73
	v_max_u32_e32 v76, v78, v71
	v_min_u32_e32 v47, v78, v71
	v_max_u32_e32 v71, v69, v79
	v_min_u32_e32 v45, v69, v79
	v_max_u32_e32 v82, v80, v77
	v_min_u32_e32 v68, v80, v77
	v_max_u32_e32 v77, v66, v67
	v_min_u32_e32 v48, v66, v67
	v_max_u32_e32 v83, v81, v84
	v_min_u32_e32 v69, v81, v84
	v_max_u32_e32 v78, v74, v85
	v_min_u32_e32 v66, v74, v85
	ds_bpermute_b32 v67, v43, v75
	ds_bpermute_b32 v79, v43, v46
	ds_bpermute_b32 v73, v43, v70
	ds_bpermute_b32 v86, v43, v44
	ds_bpermute_b32 v72, v43, v76
	ds_bpermute_b32 v85, v43, v47
	ds_bpermute_b32 v80, v43, v71
	ds_bpermute_b32 v89, v43, v45
	ds_bpermute_b32 v74, v43, v82
	ds_bpermute_b32 v87, v43, v68
	ds_bpermute_b32 v84, v43, v77
	ds_bpermute_b32 v91, v43, v48
	ds_bpermute_b32 v81, v43, v83
	ds_bpermute_b32 v90, v43, v69
	ds_bpermute_b32 v88, v43, v78
	ds_bpermute_b32 v92, v43, v66
	v_mfma_f32_16x16x32_bf16 v[28:31], v[28:31], v[32:35], v[36:39]
	s_and_saveexec_b64 s[0:1], s[4:5]
	s_cbranch_execz .LBB0_963
; __device__ void phase_peer(const Params& P, unsigned char* smem) {
;     ...
;                         for (int q = 0; q < 16; ++q) L[q] = max(L[q], R[15 - q]);
; #pragma unroll
;                         for (int d = 8; d >= 1; d >>= 1)
; #pragma unroll
;                             for (int q = 0; q < 16; ++q)
;                                 if ((q & d) == 0) { const unsigned hi_ = max(L[q], L[q + d]), lo_ = min(L[q], L[q + d]); L[q] = hi_; L[q + d] = lo_; }
;                     }
;                     if (l4 == 0) {
;                         const int tok = th * 16 + l15;
;                         float* svp = sv + ((tok * 8 + h) * 2 + (p & 1)) * 16; unsigned char* sip = si + ((tok * 8 + h) * 2 + (p & 1)) * 16;
; #pragma unroll
;                         for (int q = 0; q < 16; ++q) { const unsigned u_ = L[q] & ~127u; svp[q] = __uint_as_float((u_ & 0x80000000u) ? (u_ ^ 0x80000000u) : ~u_); sip[q] = (unsigned char)(L[q] & 127u); }
	s_waitcnt lgkmcnt(0)
	v_max_u32_e32 v32, v75, v92
	v_max_u32_e32 v33, v82, v89
	v_max_u32_e32 v35, v76, v91
	v_max_u32_e32 v36, v83, v86
	v_max_u32_e32 v39, v70, v90
	v_max_u32_e32 v70, v77, v85
	v_max_u32_e32 v71, v71, v87
	v_max_u32_e32 v76, v78, v79
	v_max_u32_e32 v46, v46, v88
	v_max_u32_e32 v68, v68, v80
	v_max_u32_e32 v47, v47, v84
	v_max_u32_e32 v69, v69, v73
	v_max_u32_e32 v44, v44, v81
	v_max_u32_e32 v48, v48, v72
	v_max_u32_e32 v45, v45, v74
	v_max_u32_e32 v66, v66, v67
	v_min_u32_e32 v34, v32, v33
	v_min_u32_e32 v37, v35, v36
	v_min_u32_e32 v75, v39, v70
	v_min_u32_e32 v77, v71, v76
	v_min_u32_e32 v80, v46, v68
	v_min_u32_e32 v73, v47, v69
	v_min_u32_e32 v72, v44, v48
	v_min_u32_e32 v67, v45, v66
	v_min_u32_e32 v38, v34, v37
	v_min_u32_e32 v78, v75, v77
	v_min_u32_e32 v82, v80, v73
	v_min_u32_e32 v74, v72, v67
	v_min_u32_e32 v79, v38, v78
	v_min_u32_e32 v81, v82, v74
	v_max_u32_e32 v38, v38, v78
	v_max_u32_e32 v74, v82, v74
	v_max_u32_e32 v34, v34, v37
	v_max_u32_e32 v37, v75, v77
	v_max_u32_e32 v73, v80, v73
	v_max_u32_e32 v67, v72, v67
	v_min_u32_e32 v78, v38, v74
	v_max_u32_e32 v38, v38, v74
	v_min_u32_e32 v74, v34, v37
	v_max_u32_e32 v34, v34, v37
	v_max_u32_e32 v37, v73, v67
	v_max_u32_e32 v32, v32, v33
	v_max_u32_e32 v33, v35, v36
	v_max_u32_e32 v35, v39, v70
	v_max_u32_e32 v36, v71, v76
	v_max_u32_e32 v46, v46, v68
	v_max_u32_e32 v47, v47, v69
	v_max_u32_e32 v44, v44, v48
	v_max_u32_e32 v45, v45, v66
	v_min_u32_e32 v72, v73, v67
	v_min_u32_e32 v67, v34, v37
	v_max_u32_e32 v37, v34, v37
	v_min_u32_e32 v34, v32, v33
	v_min_u32_e32 v39, v35, v36
	v_min_u32_e32 v68, v46, v47
	v_min_u32_e32 v48, v44, v45
	v_min_u32_e32 v70, v34, v39
	v_max_u32_e32 v34, v34, v39
	v_max_u32_e32 v39, v68, v48
	v_max_u32_e32 v32, v32, v33
	v_max_u32_e32 v33, v35, v36
	v_max_u32_e32 v35, v46, v47
	v_max_u32_e32 v36, v44, v45
	v_min_u32_e32 v66, v68, v48
	v_min_u32_e32 v48, v34, v39
	v_max_u32_e32 v39, v34, v39
	v_min_u32_e32 v34, v32, v33
	v_min_u32_e32 v44, v35, v36
	v_max_u32_e32 v32, v32, v33
	v_max_u32_e32 v33, v35, v36
	v_min_u32_e32 v45, v34, v44
	v_max_u32_e32 v44, v34, v44
	v_min_u32_e32 v34, v32, v33
	v_max_u32_e32 v36, v32, v33
	v_or_b32_e32 v32, s18, v149
	v_lshl_add_u32 v33, v32, 2, 0
	v_cmp_lt_i32_e32 vcc, -1, v34
	v_add_u32_e32 v46, 0x18000, v33
	v_add_u32_e32 v32, 0, v32
	v_cndmask_b32_e64 v33, v157, -1, vcc
	v_cmp_lt_i32_e32 vcc, -1, v36
	v_add_u32_e32 v47, 0x20000, v32
	v_and_b32_e32 v32, 0xffffff80, v34
	v_and_b32_e32 v35, 0xffffff80, v36
	v_cndmask_b32_e64 v68, v157, -1, vcc
	v_cmp_lt_i32_e32 vcc, -1, v45
	v_xor_b32_e32 v33, v33, v32
	v_xor_b32_e32 v32, v68, v35
	v_cndmask_b32_e64 v35, v157, -1, vcc
	v_cmp_lt_i32_e32 vcc, -1, v44
	v_min_u32_e32 v69, v70, v66
	v_max_u32_e32 v66, v70, v66
	v_and_b32_sdwa v68, v34, s59 dst_sel:BYTE_1 dst_unused:UNUSED_PAD src0_sel:DWORD src1_sel:DWORD
	v_and_b32_e32 v34, 0xffffff80, v45
	v_and_b32_e32 v70, 0xffffff80, v44
	v_cndmask_b32_e64 v71, v157, -1, vcc
	v_xor_b32_e32 v35, v35, v34
	v_xor_b32_e32 v34, v71, v70
	v_cmp_lt_i32_e32 vcc, -1, v48
	ds_write_b128 v46, v[32:35]
	v_and_b32_e32 v32, 0xffffff80, v48
	v_cndmask_b32_e64 v33, v157, -1, vcc
	v_cmp_lt_i32_e32 vcc, -1, v39
	v_and_b32_e32 v34, 0xffffff80, v39
	v_xor_b32_e32 v33, v33, v32
	v_cndmask_b32_e64 v35, v157, -1, vcc
	v_cmp_lt_i32_e32 vcc, -1, v69
	v_xor_b32_e32 v32, v35, v34
	v_and_b32_e32 v34, 0xffffff80, v69
	v_cndmask_b32_e64 v35, v157, -1, vcc
	v_cmp_lt_i32_e32 vcc, -1, v66
	v_and_b32_e32 v70, 0xffffff80, v66
	v_xor_b32_e32 v35, v35, v34
	v_cndmask_b32_e64 v71, v157, -1, vcc
	v_xor_b32_e32 v34, v71, v70
	v_cmp_lt_i32_e32 vcc, -1, v67
	v_min_u32_e32 v75, v74, v72
	ds_write_b128 v46, v[32:35] offset:16
	v_cndmask_b32_e64 v33, v157, -1, vcc
	v_cmp_lt_i32_e32 vcc, -1, v37
	v_max_u32_e32 v72, v74, v72
	v_and_b32_e32 v32, 0xffffff80, v67
	v_and_b32_e32 v34, 0xffffff80, v37
	v_cndmask_b32_e64 v35, v157, -1, vcc
	v_cmp_lt_i32_e32 vcc, -1, v75
	v_xor_b32_e32 v33, v33, v32
	v_xor_b32_e32 v32, v35, v34
	v_cndmask_b32_e64 v35, v157, -1, vcc
	v_cmp_lt_i32_e32 vcc, -1, v72
	v_and_b32_e32 v34, 0xffffff80, v75
	v_and_b32_e32 v70, 0xffffff80, v72
	v_cndmask_b32_e64 v71, v157, -1, vcc
	v_xor_b32_e32 v35, v35, v34
	v_xor_b32_e32 v34, v71, v70
	v_cmp_lt_i32_e32 vcc, -1, v78
	v_min_u32_e32 v83, v79, v81
	ds_write_b128 v46, v[32:35] offset:32
	v_cndmask_b32_e64 v33, v157, -1, vcc
	v_cmp_lt_i32_e32 vcc, -1, v38
	v_max_u32_e32 v79, v79, v81
	v_and_b32_e32 v32, 0xffffff80, v78
	v_and_b32_e32 v34, 0xffffff80, v38
	v_cndmask_b32_e64 v35, v157, -1, vcc
	v_cmp_lt_i32_e32 vcc, -1, v83
	v_xor_b32_e32 v33, v33, v32
	v_xor_b32_e32 v32, v35, v34
	v_cndmask_b32_e64 v35, v157, -1, vcc
	v_cmp_lt_i32_e32 vcc, -1, v79
	v_and_b32_e32 v34, 0xffffff80, v83
	v_and_b32_e32 v73, 0xffffff80, v79
	v_cndmask_b32_e64 v74, v157, -1, vcc
	v_xor_b32_e32 v35, v35, v34
	v_xor_b32_e32 v34, v74, v73
	ds_write_b128 v46, v[32:35] offset:48
	v_and_b32_sdwa v32, v83, s59 dst_sel:BYTE_1 dst_unused:UNUSED_PAD src0_sel:DWORD src1_sel:DWORD
	v_and_b32_sdwa v71, v78, s59 dst_sel:BYTE_1 dst_unused:UNUSED_PAD src0_sel:DWORD src1_sel:DWORD
	v_bitop3_b16 v32, v79, v32, s59 bitop3:0xec
	v_and_b32_sdwa v70, v75, s59 dst_sel:BYTE_1 dst_unused:UNUSED_PAD src0_sel:DWORD src1_sel:DWORD
	v_bitop3_b16 v33, v38, v71, s59 bitop3:0xec
	v_lshlrev_b32_e32 v32, 16, v32
	v_and_b32_sdwa v67, v67, s59 dst_sel:BYTE_1 dst_unused:UNUSED_PAD src0_sel:DWORD src1_sel:DWORD
	v_or_b32_sdwa v35, v33, v32 dst_sel:DWORD dst_unused:UNUSED_PAD src0_sel:WORD_0 src1_sel:DWORD
	v_bitop3_b16 v33, v72, v70, s59 bitop3:0xec
	v_and_b32_sdwa v69, v69, s59 dst_sel:BYTE_1 dst_unused:UNUSED_PAD src0_sel:DWORD src1_sel:DWORD
	v_bitop3_b16 v32, v37, v67, s59 bitop3:0xec
	v_lshlrev_b32_e32 v33, 16, v33
	v_and_b32_sdwa v48, v48, s59 dst_sel:BYTE_1 dst_unused:UNUSED_PAD src0_sel:DWORD src1_sel:DWORD
	v_or_b32_sdwa v34, v32, v33 dst_sel:DWORD dst_unused:UNUSED_PAD src0_sel:WORD_0 src1_sel:DWORD
	v_bitop3_b16 v33, v66, v69, s59 bitop3:0xec
	v_and_b32_sdwa v45, v45, s59 dst_sel:BYTE_1 dst_unused:UNUSED_PAD src0_sel:DWORD src1_sel:DWORD
	v_bitop3_b16 v32, v39, v48, s59 bitop3:0xec
	v_lshlrev_b32_e32 v33, 16, v33
	v_or_b32_sdwa v33, v32, v33 dst_sel:DWORD dst_unused:UNUSED_PAD src0_sel:WORD_0 src1_sel:DWORD
	v_bitop3_b16 v32, v36, v68, s59 bitop3:0xec
	v_bitop3_b16 v36, v44, v45, s59 bitop3:0xec
	v_lshlrev_b32_e32 v36, 16, v36
	v_or_b32_sdwa v32, v32, v36 dst_sel:DWORD dst_unused:UNUSED_PAD src0_sel:WORD_0 src1_sel:DWORD
	ds_write_b128 v47, v[32:35]
